# residual GEMM epilogues (phases 5, 8) also store their bf16 tile through the wave-private LDS image as 128-byte row pieces
# speedup vs baseline: 1.2128x; 1.0049x over previous
; DEVI unsigned pack2(float a, float b) { return (unsigned)f2bf(a) | ((unsigned)f2bf(b) << 16); }
; template <bool RESB>
; DEVI void phase_resid(const Params& p, unsigned char* smem, const u16* A, const u16* Wt, const float* res, float* ssq) {
;     ...
; #pragma unroll
;     for (int mi = 0; mi < 4; ++mi) {
;       const int m = m0 + wm * 64 + 16 * mi + col;
;       float ss = 0.f;
; #pragma unroll
;       for (int ni = 0; ni < 4; ++ni) {
;         const int n = n0 + wn * 64 + 16 * ni + 4 * quad;
;         const f32x4 v = acc[ni][mi];
;         float4 r;
;         if (RESB) {
;           const uint2 rb = *(const uint2*)(p.hn + (size_t)m * LDA + n);
;           r.x = __uint_as_float(rb.x << 16); r.y = __uint_as_float(rb.x & 0xffff0000u);
;           r.z = __uint_as_float(rb.y << 16); r.w = __uint_as_float(rb.y & 0xffff0000u);
;         } else {
;           r = *(const float4*)(res + (size_t)m * D + n);
;         }
;         float4 hv;
;         hv.x = r.x + v[0]; hv.y = r.y + v[1]; hv.z = r.z + v[2]; hv.w = r.w + v[3];
;         ss += hv.x * hv.x + hv.y * hv.y + hv.z * hv.z + hv.w * hv.w;
;         uint2 pk; pk.x = pack2(hv.x, hv.y); pk.y = pack2(hv.z, hv.w);
;         *(uint2*)(p.hn + (size_t)m * LDA + n) = pk;
;       }
;       ss += __shfl_xor(ss, 16);
;       ss += __shfl_xor(ss, 32);
;       if (quad == 0) atomicAdd(ssq + m, ss);
;     }
.LBB0_896:
	v_and_b32_e32 v200, 63, v210
	v_lshrrev_b32_e32 v201, 6, v210
	v_and_b32_e32 v202, 15, v200
	v_lshrrev_b32_e32 v203, 4, v200
	v_lshlrev_b32_e32 v204, 13, v201
	v_lshl_add_u32 v204, v202, 7, v204
	v_and_b32_e32 v205, 1, v203
	v_lshl_add_u32 v204, v205, 3, v204
	v_lshrrev_b32_e32 v205, 1, v203
	v_and_b32_e32 v206, 7, v202
	v_xor_b32_e32 v205, v205, v206
	v_xor_b32_e32 v207, 0, v205
	v_lshl_add_u32 v180, v207, 4, v204
	v_xor_b32_e32 v207, 2, v205
	v_lshl_add_u32 v181, v207, 4, v204
	v_xor_b32_e32 v207, 4, v205
	v_lshl_add_u32 v182, v207, 4, v204
	v_xor_b32_e32 v207, 6, v205
	v_lshl_add_u32 v183, v207, 4, v204
	v_lshrrev_b32_e32 v206, 3, v200
	v_and_b32_e32 v207, 7, v200
	v_lshlrev_b32_e32 v184, 13, v201
	v_lshl_add_u32 v184, v206, 7, v184
	v_lshl_add_u32 v184, v207, 4, v184
	v_xor_b32_e32 v207, v207, v206
	v_lshlrev_b32_e32 v207, 4, v207
	v_mul_lo_u32 v185, v206, s15
	v_add_u32_e32 v185, v185, v207
	v_mov_b32_e32 v186, s15
	v_lshlrev_b32_e32 v186, 3, v186
	v_ashrrev_i32_e32 v70, 1, v105
	v_and_b32_e32 v70, 0xffffffc0, v70
	v_add_u32_e32 v70, s18, v70
	v_and_or_b32 v72, v105, 15, v70
	v_and_b32_e32 v64, 64, v105
	v_lshlrev_b32_e32 v70, 2, v104
	v_ashrrev_i32_e32 v73, 31, v72
	v_readlane_b32 s72, v248, 26
	v_or3_b32 v70, v70, v64, s17
	v_lshlrev_b64 v[74:75], 12, v[72:73]
	v_readlane_b32 s73, v248, 27
	v_ashrrev_i32_e32 v71, 31, v70
	v_readlane_b32 s20, v248, 0
	v_lshl_add_u64 v[74:75], s[72:73], 0, v[74:75]
	v_lshl_add_u64 v[78:79], v[70:71], 2, v[74:75]
	global_load_dwordx4 v[74:77], v[78:79], off
	v_readlane_b32 s21, v248, 1
	v_cmp_eq_u32_e32 vcc, 0, v104
	v_readlane_b32 s74, v248, 28
	v_mov_b64_e32 v[80:81], s[20:21]
	v_mad_i64_i32 v[80:81], s[4:5], v72, s15, v[80:81]
	v_lshl_add_u64 v[80:81], v[70:71], 1, v[80:81]
	v_readlane_b32 s75, v248, 29
	v_readlane_b32 s76, v248, 30
	v_readlane_b32 s77, v248, 31
	v_readlane_b32 s78, v248, 32
	v_readlane_b32 s79, v248, 33
	v_readlane_b32 s80, v248, 34
	v_readlane_b32 s81, v248, 35
	v_readlane_b32 s82, v248, 36
	v_readlane_b32 s83, v248, 37
	v_readlane_b32 s84, v248, 38
	v_readlane_b32 s85, v248, 39
	v_readlane_b32 s86, v248, 40
	v_readlane_b32 s87, v248, 41
	v_readlane_b32 s22, v248, 2
	v_readlane_b32 s23, v248, 3
	s_waitcnt vmcnt(0)
	v_pk_add_f32 v[76:77], v[62:63], v[76:77]
	v_pk_add_f32 v[74:75], v[60:61], v[74:75]
	v_and_b32_sdwa v62, v77, v103 dst_sel:DWORD dst_unused:UNUSED_PAD src0_sel:WORD_1 src1_sel:DWORD
	v_and_b32_sdwa v61, v74, v103 dst_sel:DWORD dst_unused:UNUSED_PAD src0_sel:WORD_1 src1_sel:DWORD
	v_and_b32_sdwa v63, v75, v103 dst_sel:DWORD dst_unused:UNUSED_PAD src0_sel:WORD_1 src1_sel:DWORD
	v_and_b32_sdwa v60, v76, v103 dst_sel:DWORD dst_unused:UNUSED_PAD src0_sel:WORD_1 src1_sel:DWORD
	v_add3_u32 v64, v74, v61, s16
	v_add3_u32 v61, v77, v62, s16
	v_add3_u32 v62, v75, v63, s16
	v_add3_u32 v60, v76, v60, s16
	v_and_b32_e32 v61, 0xffff0000, v61
	v_and_b32_e32 v62, 0xffff0000, v62
	v_or_b32_sdwa v61, v61, v60 dst_sel:DWORD dst_unused:UNUSED_PAD src0_sel:DWORD src1_sel:WORD_1
	v_or_b32_sdwa v60, v62, v64 dst_sel:DWORD dst_unused:UNUSED_PAD src0_sel:DWORD src1_sel:WORD_1
	v_readfirstlane_b32 s98, v80
	v_readfirstlane_b32 s99, v81
	ds_write_b64 v180, v[60:61]
	global_load_dwordx4 v[60:63], v[78:79], off offset:64
	v_pk_mul_f32 v[74:75], v[74:75], v[74:75]
	v_pk_mul_f32 v[76:77], v[76:77], v[76:77]
	s_waitcnt vmcnt(0)
	v_pk_add_f32 v[62:63], v[58:59], v[62:63]
	v_pk_add_f32 v[60:61], v[56:57], v[60:61]
	v_and_b32_sdwa v58, v63, v103 dst_sel:DWORD dst_unused:UNUSED_PAD src0_sel:WORD_1 src1_sel:DWORD
	v_and_b32_sdwa v57, v60, v103 dst_sel:DWORD dst_unused:UNUSED_PAD src0_sel:WORD_1 src1_sel:DWORD
	v_and_b32_sdwa v59, v61, v103 dst_sel:DWORD dst_unused:UNUSED_PAD src0_sel:WORD_1 src1_sel:DWORD
	v_and_b32_sdwa v56, v62, v103 dst_sel:DWORD dst_unused:UNUSED_PAD src0_sel:WORD_1 src1_sel:DWORD
	v_add3_u32 v64, v60, v57, s16
	v_add3_u32 v57, v63, v58, s16
	v_add3_u32 v58, v61, v59, s16
	v_add3_u32 v56, v62, v56, s16
	v_and_b32_e32 v57, 0xffff0000, v57
	v_and_b32_e32 v58, 0xffff0000, v58
	v_or_b32_sdwa v57, v57, v56 dst_sel:DWORD dst_unused:UNUSED_PAD src0_sel:DWORD src1_sel:WORD_1
	v_or_b32_sdwa v56, v58, v64 dst_sel:DWORD dst_unused:UNUSED_PAD src0_sel:DWORD src1_sel:WORD_1
	ds_write_b64 v181, v[56:57]
	global_load_dwordx4 v[56:59], v[78:79], off offset:128
	v_xor_b32_e32 v64, 32, v102
	v_pk_mul_f32 v[60:61], v[60:61], v[60:61]
	v_pk_mul_f32 v[62:63], v[62:63], v[62:63]
	v_add_f32_e32 v60, v60, v61
	v_add_f32_e32 v60, v60, v62
	v_add_f32_e32 v60, v60, v63
	s_waitcnt vmcnt(0)
	v_pk_add_f32 v[58:59], v[54:55], v[58:59]
	v_pk_add_f32 v[82:83], v[52:53], v[56:57]
	v_and_b32_sdwa v54, v59, v103 dst_sel:DWORD dst_unused:UNUSED_PAD src0_sel:WORD_1 src1_sel:DWORD
	v_and_b32_sdwa v53, v82, v103 dst_sel:DWORD dst_unused:UNUSED_PAD src0_sel:WORD_1 src1_sel:DWORD
	v_and_b32_sdwa v55, v83, v103 dst_sel:DWORD dst_unused:UNUSED_PAD src0_sel:WORD_1 src1_sel:DWORD
	v_and_b32_sdwa v52, v58, v103 dst_sel:DWORD dst_unused:UNUSED_PAD src0_sel:WORD_1 src1_sel:DWORD
	v_add3_u32 v56, v82, v53, s16
	v_add3_u32 v53, v59, v54, s16
	v_add3_u32 v54, v83, v55, s16
	v_add3_u32 v52, v58, v52, s16
	v_and_b32_e32 v53, 0xffff0000, v53
	v_and_b32_e32 v54, 0xffff0000, v54
	v_or_b32_sdwa v53, v53, v52 dst_sel:DWORD dst_unused:UNUSED_PAD src0_sel:DWORD src1_sel:WORD_1
	v_or_b32_sdwa v52, v54, v56 dst_sel:DWORD dst_unused:UNUSED_PAD src0_sel:DWORD src1_sel:WORD_1
	ds_write_b64 v182, v[52:53]
	global_load_dwordx4 v[54:57], v[78:79], off offset:192
	v_and_b32_e32 v53, 64, v102
	v_xor_b32_e32 v52, 16, v102
	v_add_u32_e32 v53, 64, v53
	v_cmp_lt_i32_e64 s[4:5], v52, v53
	v_pk_mul_f32 v[58:59], v[58:59], v[58:59]
	s_waitcnt vmcnt(0)
; DEVI unsigned pack2(float a, float b) { return (unsigned)f2bf(a) | ((unsigned)f2bf(b) << 16); }
; template <bool RESB>
; DEVI void phase_resid(const Params& p, unsigned char* smem, const u16* A, const u16* Wt, const float* res, float* ssq) {
;     ...
; #pragma unroll
;     for (int mi = 0; mi < 4; ++mi) {
;       const int m = m0 + wm * 64 + 16 * mi + col;
;       float ss = 0.f;
; #pragma unroll
;       for (int ni = 0; ni < 4; ++ni) {
;         const int n = n0 + wn * 64 + 16 * ni + 4 * quad;
;         const f32x4 v = acc[ni][mi];
;         float4 r;
;         if (RESB) {
;           const uint2 rb = *(const uint2*)(p.hn + (size_t)m * LDA + n);
;           r.x = __uint_as_float(rb.x << 16); r.y = __uint_as_float(rb.x & 0xffff0000u);
;           r.z = __uint_as_float(rb.y << 16); r.w = __uint_as_float(rb.y & 0xffff0000u);
;         } else {
;           r = *(const float4*)(res + (size_t)m * D + n);
;         }
;         float4 hv;
;         hv.x = r.x + v[0]; hv.y = r.y + v[1]; hv.z = r.z + v[2]; hv.w = r.w + v[3];
;         ss += hv.x * hv.x + hv.y * hv.y + hv.z * hv.z + hv.w * hv.w;
;         uint2 pk; pk.x = pack2(hv.x, hv.y); pk.y = pack2(hv.z, hv.w);
;         *(uint2*)(p.hn + (size_t)m * LDA + n) = pk;
;       }
;       ss += __shfl_xor(ss, 16);
;       ss += __shfl_xor(ss, 32);
;       if (quad == 0) atomicAdd(ssq + m, ss);
;     }
	v_pk_add_f32 v[48:49], v[48:49], v[54:55]
	v_cndmask_b32_e64 v52, v102, v52, s[4:5]
	v_cmp_lt_i32_e64 s[4:5], v64, v53
	v_lshlrev_b32_e32 v53, 2, v52
	v_pk_add_f32 v[50:51], v[50:51], v[56:57]
	v_cndmask_b32_e64 v64, v102, v64, s[4:5]
	v_lshlrev_b32_e32 v52, 2, v64
	v_add_f32_e32 v64, v74, v75
	v_add_f32_e32 v64, v64, v76
	v_add_f32_e32 v64, v64, v77
	v_add_f32_e32 v62, v64, v60
	v_pk_mul_f32 v[60:61], v[82:83], v[82:83]
	v_pk_mul_f32 v[56:57], v[48:49], v[48:49]
	v_add_f32_e32 v60, v60, v61
	v_add_f32_e32 v58, v60, v58
	v_add_f32_e32 v58, v58, v59
	v_pk_mul_f32 v[54:55], v[50:51], v[50:51]
	v_and_b32_sdwa v59, v50, v103 dst_sel:DWORD dst_unused:UNUSED_PAD src0_sel:WORD_1 src1_sel:DWORD
	v_add_f32_e32 v56, v56, v57
	v_add3_u32 v57, v50, v59, s16
	v_add_f32_e32 v50, v56, v54
	v_add_f32_e32 v58, v62, v58
	v_add_f32_e32 v50, v50, v55
	v_add_f32_e32 v50, v58, v50
	ds_bpermute_b32 v55, v53, v50
	v_and_b32_sdwa v61, v51, v103 dst_sel:DWORD dst_unused:UNUSED_PAD src0_sel:WORD_1 src1_sel:DWORD
	v_and_b32_sdwa v54, v49, v103 dst_sel:DWORD dst_unused:UNUSED_PAD src0_sel:WORD_1 src1_sel:DWORD
	v_add3_u32 v51, v51, v61, s16
	v_add3_u32 v49, v49, v54, s16
	s_waitcnt lgkmcnt(0)
	v_add_f32_e32 v50, v50, v55
	v_and_b32_e32 v54, 0xffff0000, v51
	ds_bpermute_b32 v51, v52, v50
	v_and_b32_sdwa v60, v48, v103 dst_sel:DWORD dst_unused:UNUSED_PAD src0_sel:WORD_1 src1_sel:DWORD
	v_add3_u32 v48, v48, v60, s16
	v_and_b32_e32 v56, 0xffff0000, v49
	v_or_b32_sdwa v49, v54, v57 dst_sel:DWORD dst_unused:UNUSED_PAD src0_sel:DWORD src1_sel:WORD_1
	v_or_b32_sdwa v48, v56, v48 dst_sel:DWORD dst_unused:UNUSED_PAD src0_sel:DWORD src1_sel:WORD_1
	ds_write_b64 v183, v[48:49]
	v_lshl_add_u64 v[48:49], v[72:73], 2, s[48:49]
	s_and_saveexec_b64 s[4:5], vcc
	s_cbranch_execz .LBB0_898
	s_waitcnt lgkmcnt(0)
	v_add_f32_e32 v50, v50, v51
	global_atomic_add_f32 v[48:49], v50, off
.LBB0_898:
	s_or_b64 exec, exec, s[4:5]
	v_or_b32_e32 v50, 16, v72
	s_waitcnt lgkmcnt(0)
	v_ashrrev_i32_e32 v51, 31, v50
	v_readlane_b32 s72, v248, 26
	v_lshlrev_b64 v[54:55], 12, v[50:51]
	v_readlane_b32 s73, v248, 27
	v_readlane_b32 s20, v248, 0
	v_readlane_b32 s21, v248, 1
	v_lshl_add_u64 v[54:55], s[72:73], 0, v[54:55]
	v_lshl_add_u64 v[58:59], v[70:71], 2, v[54:55]
	global_load_dwordx4 v[54:57], v[58:59], off
	v_mov_b64_e32 v[60:61], s[20:21]
	v_mad_i64_i32 v[50:51], s[4:5], v50, s15, v[60:61]
	v_lshl_add_u64 v[50:51], v[70:71], 1, v[50:51]
	v_readlane_b32 s74, v248, 28
	v_readlane_b32 s75, v248, 29
	v_readlane_b32 s76, v248, 30
	v_readlane_b32 s77, v248, 31
	v_readlane_b32 s78, v248, 32
	v_readlane_b32 s79, v248, 33
	v_readlane_b32 s80, v248, 34
	v_readlane_b32 s81, v248, 35
	v_readlane_b32 s82, v248, 36
	v_readlane_b32 s83, v248, 37
	v_readlane_b32 s84, v248, 38
	v_readlane_b32 s85, v248, 39
	v_readlane_b32 s86, v248, 40
	v_readlane_b32 s87, v248, 41
	v_readlane_b32 s22, v248, 2
	v_readlane_b32 s23, v248, 3
	s_waitcnt vmcnt(0)
	v_pk_add_f32 v[56:57], v[46:47], v[56:57]
	v_pk_add_f32 v[54:55], v[44:45], v[54:55]
	v_and_b32_sdwa v46, v57, v103 dst_sel:DWORD dst_unused:UNUSED_PAD src0_sel:WORD_1 src1_sel:DWORD
	v_and_b32_sdwa v45, v54, v103 dst_sel:DWORD dst_unused:UNUSED_PAD src0_sel:WORD_1 src1_sel:DWORD
	v_and_b32_sdwa v47, v55, v103 dst_sel:DWORD dst_unused:UNUSED_PAD src0_sel:WORD_1 src1_sel:DWORD
	v_and_b32_sdwa v44, v56, v103 dst_sel:DWORD dst_unused:UNUSED_PAD src0_sel:WORD_1 src1_sel:DWORD
	v_add3_u32 v60, v54, v45, s16
	v_add3_u32 v45, v57, v46, s16
	v_add3_u32 v46, v55, v47, s16
	v_add3_u32 v44, v56, v44, s16
	v_and_b32_e32 v45, 0xffff0000, v45
	v_and_b32_e32 v46, 0xffff0000, v46
	v_or_b32_sdwa v45, v45, v44 dst_sel:DWORD dst_unused:UNUSED_PAD src0_sel:DWORD src1_sel:WORD_1
	v_or_b32_sdwa v44, v46, v60 dst_sel:DWORD dst_unused:UNUSED_PAD src0_sel:DWORD src1_sel:WORD_1
	ds_write_b64 v180, v[44:45] offset:2048
	global_load_dwordx4 v[44:47], v[58:59], off offset:64
	v_pk_mul_f32 v[54:55], v[54:55], v[54:55]
	v_pk_mul_f32 v[56:57], v[56:57], v[56:57]
	v_add_f32_e32 v54, v54, v55
	v_add_f32_e32 v54, v54, v56
	v_add_f32_e32 v54, v54, v57
	s_waitcnt vmcnt(0)
	v_pk_add_f32 v[46:47], v[42:43], v[46:47]
	v_pk_add_f32 v[44:45], v[40:41], v[44:45]
	v_and_b32_sdwa v42, v47, v103 dst_sel:DWORD dst_unused:UNUSED_PAD src0_sel:WORD_1 src1_sel:DWORD
	v_and_b32_sdwa v41, v44, v103 dst_sel:DWORD dst_unused:UNUSED_PAD src0_sel:WORD_1 src1_sel:DWORD
	v_and_b32_sdwa v43, v45, v103 dst_sel:DWORD dst_unused:UNUSED_PAD src0_sel:WORD_1 src1_sel:DWORD
	v_and_b32_sdwa v40, v46, v103 dst_sel:DWORD dst_unused:UNUSED_PAD src0_sel:WORD_1 src1_sel:DWORD
	v_add3_u32 v60, v44, v41, s16
	v_add3_u32 v41, v47, v42, s16
	v_add3_u32 v42, v45, v43, s16
	v_add3_u32 v40, v46, v40, s16
	v_and_b32_e32 v41, 0xffff0000, v41
	v_and_b32_e32 v42, 0xffff0000, v42
	v_or_b32_sdwa v41, v41, v40 dst_sel:DWORD dst_unused:UNUSED_PAD src0_sel:DWORD src1_sel:WORD_1
	v_or_b32_sdwa v40, v42, v60 dst_sel:DWORD dst_unused:UNUSED_PAD src0_sel:DWORD src1_sel:WORD_1
	ds_write_b64 v181, v[40:41] offset:2048
	global_load_dwordx4 v[40:43], v[58:59], off offset:128
	v_pk_mul_f32 v[44:45], v[44:45], v[44:45]
	v_pk_mul_f32 v[46:47], v[46:47], v[46:47]
	v_add_f32_e32 v44, v44, v45
	v_add_f32_e32 v44, v44, v46
	v_add_f32_e32 v44, v44, v47
	v_add_f32_e32 v44, v54, v44
	s_waitcnt vmcnt(0)
; DEVI unsigned pack2(float a, float b) { return (unsigned)f2bf(a) | ((unsigned)f2bf(b) << 16); }
; template <bool RESB>
; DEVI void phase_resid(const Params& p, unsigned char* smem, const u16* A, const u16* Wt, const float* res, float* ssq) {
;     ...
; #pragma unroll
;     for (int mi = 0; mi < 4; ++mi) {
;       const int m = m0 + wm * 64 + 16 * mi + col;
;       float ss = 0.f;
; #pragma unroll
;       for (int ni = 0; ni < 4; ++ni) {
;         const int n = n0 + wn * 64 + 16 * ni + 4 * quad;
;         const f32x4 v = acc[ni][mi];
;         float4 r;
;         if (RESB) {
;           const uint2 rb = *(const uint2*)(p.hn + (size_t)m * LDA + n);
;           r.x = __uint_as_float(rb.x << 16); r.y = __uint_as_float(rb.x & 0xffff0000u);
;           r.z = __uint_as_float(rb.y << 16); r.w = __uint_as_float(rb.y & 0xffff0000u);
;         } else {
;           r = *(const float4*)(res + (size_t)m * D + n);
;         }
;         float4 hv;
;         hv.x = r.x + v[0]; hv.y = r.y + v[1]; hv.z = r.z + v[2]; hv.w = r.w + v[3];
;         ss += hv.x * hv.x + hv.y * hv.y + hv.z * hv.z + hv.w * hv.w;
;         uint2 pk; pk.x = pack2(hv.x, hv.y); pk.y = pack2(hv.z, hv.w);
;         *(uint2*)(p.hn + (size_t)m * LDA + n) = pk;
;       }
;       ss += __shfl_xor(ss, 16);
;       ss += __shfl_xor(ss, 32);
;       if (quad == 0) atomicAdd(ssq + m, ss);
;     }
	v_pk_add_f32 v[42:43], v[38:39], v[42:43]
	v_pk_add_f32 v[40:41], v[36:37], v[40:41]
	v_and_b32_sdwa v38, v43, v103 dst_sel:DWORD dst_unused:UNUSED_PAD src0_sel:WORD_1 src1_sel:DWORD
	v_and_b32_sdwa v37, v40, v103 dst_sel:DWORD dst_unused:UNUSED_PAD src0_sel:WORD_1 src1_sel:DWORD
	v_and_b32_sdwa v39, v41, v103 dst_sel:DWORD dst_unused:UNUSED_PAD src0_sel:WORD_1 src1_sel:DWORD
	v_and_b32_sdwa v36, v42, v103 dst_sel:DWORD dst_unused:UNUSED_PAD src0_sel:WORD_1 src1_sel:DWORD
	v_add3_u32 v60, v40, v37, s16
	v_add3_u32 v37, v43, v38, s16
	v_add3_u32 v38, v41, v39, s16
	v_add3_u32 v36, v42, v36, s16
	v_and_b32_e32 v37, 0xffff0000, v37
	v_and_b32_e32 v38, 0xffff0000, v38
	v_or_b32_sdwa v37, v37, v36 dst_sel:DWORD dst_unused:UNUSED_PAD src0_sel:DWORD src1_sel:WORD_1
	v_or_b32_sdwa v36, v38, v60 dst_sel:DWORD dst_unused:UNUSED_PAD src0_sel:DWORD src1_sel:WORD_1
	ds_write_b64 v182, v[36:37] offset:2048
	global_load_dwordx4 v[36:39], v[58:59], off offset:192
	v_pk_mul_f32 v[40:41], v[40:41], v[40:41]
	v_pk_mul_f32 v[42:43], v[42:43], v[42:43]
	v_add_f32_e32 v40, v40, v41
	v_add_f32_e32 v40, v40, v42
	v_add_f32_e32 v40, v40, v43
	v_add_f32_e32 v40, v44, v40
	s_waitcnt vmcnt(0)
	v_pk_add_f32 v[32:33], v[32:33], v[36:37]
	v_pk_add_f32 v[34:35], v[34:35], v[38:39]
	v_pk_mul_f32 v[38:39], v[32:33], v[32:33]
	v_pk_mul_f32 v[36:37], v[34:35], v[34:35]
	v_and_b32_sdwa v42, v32, v103 dst_sel:DWORD dst_unused:UNUSED_PAD src0_sel:WORD_1 src1_sel:DWORD
	v_add_f32_e32 v38, v38, v39
	v_add3_u32 v39, v32, v42, s16
	v_add_f32_e32 v32, v38, v36
	v_add_f32_e32 v32, v32, v37
	v_add_f32_e32 v32, v40, v32
	ds_bpermute_b32 v37, v53, v32
	v_and_b32_sdwa v36, v35, v103 dst_sel:DWORD dst_unused:UNUSED_PAD src0_sel:WORD_1 src1_sel:DWORD
	v_and_b32_sdwa v38, v33, v103 dst_sel:DWORD dst_unused:UNUSED_PAD src0_sel:WORD_1 src1_sel:DWORD
	v_add3_u32 v35, v35, v36, s16
	v_add3_u32 v36, v33, v38, s16
	s_waitcnt lgkmcnt(0)
	v_add_f32_e32 v32, v32, v37
	ds_bpermute_b32 v33, v52, v32
	v_and_b32_sdwa v41, v34, v103 dst_sel:DWORD dst_unused:UNUSED_PAD src0_sel:WORD_1 src1_sel:DWORD
	v_add3_u32 v34, v34, v41, s16
	v_and_b32_e32 v35, 0xffff0000, v35
	v_and_b32_e32 v36, 0xffff0000, v36
	v_or_b32_sdwa v35, v35, v34 dst_sel:DWORD dst_unused:UNUSED_PAD src0_sel:DWORD src1_sel:WORD_1
	v_or_b32_sdwa v34, v36, v39 dst_sel:DWORD dst_unused:UNUSED_PAD src0_sel:DWORD src1_sel:WORD_1
	ds_write_b64 v183, v[34:35] offset:2048
	s_and_saveexec_b64 s[4:5], vcc
	s_cbranch_execz .LBB0_900
	s_waitcnt lgkmcnt(0)
	v_add_f32_e32 v32, v32, v33
	global_atomic_add_f32 v[48:49], v32, off offset:64
.LBB0_900:
	s_or_b64 exec, exec, s[4:5]
	v_or_b32_e32 v36, 32, v72
	v_ashrrev_i32_e32 v37, 31, v36
	v_readlane_b32 s72, v248, 26
	s_waitcnt lgkmcnt(0)
	v_lshlrev_b64 v[32:33], 12, v[36:37]
	v_readlane_b32 s73, v248, 27
	v_readlane_b32 s20, v248, 0
	v_readlane_b32 s21, v248, 1
	v_lshl_add_u64 v[32:33], s[72:73], 0, v[32:33]
	v_lshl_add_u64 v[38:39], v[70:71], 2, v[32:33]
	global_load_dwordx4 v[32:35], v[38:39], off
	v_mov_b64_e32 v[40:41], s[20:21]
	v_mad_i64_i32 v[36:37], s[4:5], v36, s15, v[40:41]
	v_lshl_add_u64 v[36:37], v[70:71], 1, v[36:37]
	v_readlane_b32 s74, v248, 28
	v_readlane_b32 s75, v248, 29
	v_readlane_b32 s76, v248, 30
	v_readlane_b32 s77, v248, 31
	v_readlane_b32 s78, v248, 32
	v_readlane_b32 s79, v248, 33
	v_readlane_b32 s80, v248, 34
	v_readlane_b32 s81, v248, 35
	v_readlane_b32 s82, v248, 36
	v_readlane_b32 s83, v248, 37
	v_readlane_b32 s84, v248, 38
	v_readlane_b32 s85, v248, 39
	v_readlane_b32 s86, v248, 40
	v_readlane_b32 s87, v248, 41
	v_readlane_b32 s22, v248, 2
	v_readlane_b32 s23, v248, 3
	s_waitcnt vmcnt(0)
	v_pk_add_f32 v[34:35], v[30:31], v[34:35]
	v_pk_add_f32 v[32:33], v[28:29], v[32:33]
	v_and_b32_sdwa v30, v35, v103 dst_sel:DWORD dst_unused:UNUSED_PAD src0_sel:WORD_1 src1_sel:DWORD
	v_and_b32_sdwa v29, v32, v103 dst_sel:DWORD dst_unused:UNUSED_PAD src0_sel:WORD_1 src1_sel:DWORD
	v_and_b32_sdwa v31, v33, v103 dst_sel:DWORD dst_unused:UNUSED_PAD src0_sel:WORD_1 src1_sel:DWORD
	v_and_b32_sdwa v28, v34, v103 dst_sel:DWORD dst_unused:UNUSED_PAD src0_sel:WORD_1 src1_sel:DWORD
	v_add3_u32 v40, v32, v29, s16
	v_add3_u32 v29, v35, v30, s16
	v_add3_u32 v30, v33, v31, s16
	v_add3_u32 v28, v34, v28, s16
	v_and_b32_e32 v29, 0xffff0000, v29
	v_and_b32_e32 v30, 0xffff0000, v30
	v_or_b32_sdwa v29, v29, v28 dst_sel:DWORD dst_unused:UNUSED_PAD src0_sel:DWORD src1_sel:WORD_1
	v_or_b32_sdwa v28, v30, v40 dst_sel:DWORD dst_unused:UNUSED_PAD src0_sel:DWORD src1_sel:WORD_1
	ds_write_b64 v180, v[28:29] offset:4096
	global_load_dwordx4 v[28:31], v[38:39], off offset:64
	v_pk_mul_f32 v[32:33], v[32:33], v[32:33]
	v_pk_mul_f32 v[34:35], v[34:35], v[34:35]
	v_add_f32_e32 v32, v32, v33
	v_add_f32_e32 v32, v32, v34
	v_add_f32_e32 v32, v32, v35
	s_waitcnt vmcnt(0)
	v_pk_add_f32 v[30:31], v[26:27], v[30:31]
	v_pk_add_f32 v[28:29], v[24:25], v[28:29]
	v_and_b32_sdwa v26, v31, v103 dst_sel:DWORD dst_unused:UNUSED_PAD src0_sel:WORD_1 src1_sel:DWORD
	v_and_b32_sdwa v25, v28, v103 dst_sel:DWORD dst_unused:UNUSED_PAD src0_sel:WORD_1 src1_sel:DWORD
	v_and_b32_sdwa v27, v29, v103 dst_sel:DWORD dst_unused:UNUSED_PAD src0_sel:WORD_1 src1_sel:DWORD
	v_and_b32_sdwa v24, v30, v103 dst_sel:DWORD dst_unused:UNUSED_PAD src0_sel:WORD_1 src1_sel:DWORD
	v_add3_u32 v40, v28, v25, s16
	v_add3_u32 v25, v31, v26, s16
	v_add3_u32 v26, v29, v27, s16
	v_add3_u32 v24, v30, v24, s16
	v_and_b32_e32 v25, 0xffff0000, v25
	v_and_b32_e32 v26, 0xffff0000, v26
	v_or_b32_sdwa v25, v25, v24 dst_sel:DWORD dst_unused:UNUSED_PAD src0_sel:DWORD src1_sel:WORD_1
	v_or_b32_sdwa v24, v26, v40 dst_sel:DWORD dst_unused:UNUSED_PAD src0_sel:DWORD src1_sel:WORD_1
	ds_write_b64 v181, v[24:25] offset:4096
	global_load_dwordx4 v[24:27], v[38:39], off offset:128
	v_pk_mul_f32 v[28:29], v[28:29], v[28:29]
	v_pk_mul_f32 v[30:31], v[30:31], v[30:31]
	v_add_f32_e32 v28, v28, v29
	v_add_f32_e32 v28, v28, v30
	v_add_f32_e32 v28, v28, v31
	v_add_f32_e32 v28, v32, v28
	s_waitcnt vmcnt(0)
; DEVI unsigned pack2(float a, float b) { return (unsigned)f2bf(a) | ((unsigned)f2bf(b) << 16); }
; template <bool RESB>
; DEVI void phase_resid(const Params& p, unsigned char* smem, const u16* A, const u16* Wt, const float* res, float* ssq) {
;     ...
; #pragma unroll
;     for (int mi = 0; mi < 4; ++mi) {
;       const int m = m0 + wm * 64 + 16 * mi + col;
;       float ss = 0.f;
; #pragma unroll
;       for (int ni = 0; ni < 4; ++ni) {
;         const int n = n0 + wn * 64 + 16 * ni + 4 * quad;
;         const f32x4 v = acc[ni][mi];
;         float4 r;
;         if (RESB) {
;           const uint2 rb = *(const uint2*)(p.hn + (size_t)m * LDA + n);
;           r.x = __uint_as_float(rb.x << 16); r.y = __uint_as_float(rb.x & 0xffff0000u);
;           r.z = __uint_as_float(rb.y << 16); r.w = __uint_as_float(rb.y & 0xffff0000u);
;         } else {
;           r = *(const float4*)(res + (size_t)m * D + n);
;         }
;         float4 hv;
;         hv.x = r.x + v[0]; hv.y = r.y + v[1]; hv.z = r.z + v[2]; hv.w = r.w + v[3];
;         ss += hv.x * hv.x + hv.y * hv.y + hv.z * hv.z + hv.w * hv.w;
;         uint2 pk; pk.x = pack2(hv.x, hv.y); pk.y = pack2(hv.z, hv.w);
;         *(uint2*)(p.hn + (size_t)m * LDA + n) = pk;
;       }
;       ss += __shfl_xor(ss, 16);
;       ss += __shfl_xor(ss, 32);
;       if (quad == 0) atomicAdd(ssq + m, ss);
;     }
	v_pk_add_f32 v[26:27], v[22:23], v[26:27]
	v_pk_add_f32 v[24:25], v[20:21], v[24:25]
	v_and_b32_sdwa v22, v27, v103 dst_sel:DWORD dst_unused:UNUSED_PAD src0_sel:WORD_1 src1_sel:DWORD
	v_and_b32_sdwa v21, v24, v103 dst_sel:DWORD dst_unused:UNUSED_PAD src0_sel:WORD_1 src1_sel:DWORD
	v_and_b32_sdwa v23, v25, v103 dst_sel:DWORD dst_unused:UNUSED_PAD src0_sel:WORD_1 src1_sel:DWORD
	v_and_b32_sdwa v20, v26, v103 dst_sel:DWORD dst_unused:UNUSED_PAD src0_sel:WORD_1 src1_sel:DWORD
	v_add3_u32 v40, v24, v21, s16
	v_add3_u32 v21, v27, v22, s16
	v_add3_u32 v22, v25, v23, s16
	v_add3_u32 v20, v26, v20, s16
	v_and_b32_e32 v21, 0xffff0000, v21
	v_and_b32_e32 v22, 0xffff0000, v22
	v_or_b32_sdwa v21, v21, v20 dst_sel:DWORD dst_unused:UNUSED_PAD src0_sel:DWORD src1_sel:WORD_1
	v_or_b32_sdwa v20, v22, v40 dst_sel:DWORD dst_unused:UNUSED_PAD src0_sel:DWORD src1_sel:WORD_1
	ds_write_b64 v182, v[20:21] offset:4096
	global_load_dwordx4 v[20:23], v[38:39], off offset:192
	v_pk_mul_f32 v[24:25], v[24:25], v[24:25]
	v_pk_mul_f32 v[26:27], v[26:27], v[26:27]
	v_add_f32_e32 v24, v24, v25
	v_add_f32_e32 v24, v24, v26
	v_add_f32_e32 v24, v24, v27
	v_add_f32_e32 v24, v28, v24
	s_waitcnt vmcnt(0)
	v_pk_add_f32 v[16:17], v[16:17], v[20:21]
	v_pk_add_f32 v[18:19], v[18:19], v[22:23]
	v_pk_mul_f32 v[22:23], v[16:17], v[16:17]
	v_pk_mul_f32 v[20:21], v[18:19], v[18:19]
	v_and_b32_sdwa v26, v16, v103 dst_sel:DWORD dst_unused:UNUSED_PAD src0_sel:WORD_1 src1_sel:DWORD
	v_add_f32_e32 v22, v22, v23
	v_add3_u32 v23, v16, v26, s16
	v_add_f32_e32 v16, v22, v20
	v_add_f32_e32 v16, v16, v21
	v_add_f32_e32 v16, v24, v16
	ds_bpermute_b32 v21, v53, v16
	v_and_b32_sdwa v20, v19, v103 dst_sel:DWORD dst_unused:UNUSED_PAD src0_sel:WORD_1 src1_sel:DWORD
	v_and_b32_sdwa v22, v17, v103 dst_sel:DWORD dst_unused:UNUSED_PAD src0_sel:WORD_1 src1_sel:DWORD
	v_add3_u32 v19, v19, v20, s16
	v_add3_u32 v20, v17, v22, s16
	s_waitcnt lgkmcnt(0)
	v_add_f32_e32 v16, v16, v21
	ds_bpermute_b32 v17, v52, v16
	v_and_b32_sdwa v25, v18, v103 dst_sel:DWORD dst_unused:UNUSED_PAD src0_sel:WORD_1 src1_sel:DWORD
	v_add3_u32 v18, v18, v25, s16
	v_and_b32_e32 v19, 0xffff0000, v19
	v_and_b32_e32 v20, 0xffff0000, v20
	v_or_b32_sdwa v19, v19, v18 dst_sel:DWORD dst_unused:UNUSED_PAD src0_sel:DWORD src1_sel:WORD_1
	v_or_b32_sdwa v18, v20, v23 dst_sel:DWORD dst_unused:UNUSED_PAD src0_sel:DWORD src1_sel:WORD_1
	ds_write_b64 v183, v[18:19] offset:4096
	s_and_saveexec_b64 s[4:5], vcc
	s_cbranch_execz .LBB0_902
	s_waitcnt lgkmcnt(0)
	v_add_f32_e32 v16, v16, v17
	global_atomic_add_f32 v[48:49], v16, off offset:128
; DEVI unsigned pack2(float a, float b) { return (unsigned)f2bf(a) | ((unsigned)f2bf(b) << 16); }
; template <bool RESB>
; DEVI void phase_resid(const Params& p, unsigned char* smem, const u16* A, const u16* Wt, const float* res, float* ssq) {
;     ...
; #pragma unroll
;     for (int mi = 0; mi < 4; ++mi) {
;       const int m = m0 + wm * 64 + 16 * mi + col;
;       float ss = 0.f;
; #pragma unroll
;       for (int ni = 0; ni < 4; ++ni) {
;         const int n = n0 + wn * 64 + 16 * ni + 4 * quad;
;         const f32x4 v = acc[ni][mi];
;         float4 r;
;         if (RESB) {
;           const uint2 rb = *(const uint2*)(p.hn + (size_t)m * LDA + n);
;           r.x = __uint_as_float(rb.x << 16); r.y = __uint_as_float(rb.x & 0xffff0000u);
;           r.z = __uint_as_float(rb.y << 16); r.w = __uint_as_float(rb.y & 0xffff0000u);
;         } else {
;           r = *(const float4*)(res + (size_t)m * D + n);
;         }
;         float4 hv;
;         hv.x = r.x + v[0]; hv.y = r.y + v[1]; hv.z = r.z + v[2]; hv.w = r.w + v[3];
;         ss += hv.x * hv.x + hv.y * hv.y + hv.z * hv.z + hv.w * hv.w;
;         uint2 pk; pk.x = pack2(hv.x, hv.y); pk.y = pack2(hv.z, hv.w);
;         *(uint2*)(p.hn + (size_t)m * LDA + n) = pk;
;       }
;       ss += __shfl_xor(ss, 16);
;       ss += __shfl_xor(ss, 32);
;       if (quad == 0) atomicAdd(ssq + m, ss);
;     }
.LBB0_902:
	s_or_b64 exec, exec, s[4:5]
	v_or_b32_e32 v20, 48, v72
	v_ashrrev_i32_e32 v21, 31, v20
	v_readlane_b32 s72, v248, 26
	s_waitcnt lgkmcnt(0)
	v_lshlrev_b64 v[16:17], 12, v[20:21]
	v_readlane_b32 s73, v248, 27
	v_readlane_b32 s20, v248, 0
	v_readlane_b32 s21, v248, 1
	v_lshl_add_u64 v[16:17], s[72:73], 0, v[16:17]
	v_lshl_add_u64 v[22:23], v[70:71], 2, v[16:17]
	global_load_dwordx4 v[16:19], v[22:23], off
	v_mov_b64_e32 v[24:25], s[20:21]
	v_mad_i64_i32 v[20:21], s[4:5], v20, s15, v[24:25]
	v_lshl_add_u64 v[20:21], v[70:71], 1, v[20:21]
	v_readlane_b32 s74, v248, 28
	v_readlane_b32 s75, v248, 29
	v_readlane_b32 s76, v248, 30
	v_readlane_b32 s77, v248, 31
	v_readlane_b32 s78, v248, 32
	v_readlane_b32 s79, v248, 33
	v_readlane_b32 s80, v248, 34
	v_readlane_b32 s81, v248, 35
	v_readlane_b32 s82, v248, 36
	v_readlane_b32 s83, v248, 37
	v_readlane_b32 s84, v248, 38
	v_readlane_b32 s85, v248, 39
	v_readlane_b32 s86, v248, 40
	v_readlane_b32 s87, v248, 41
	v_readlane_b32 s22, v248, 2
	v_readlane_b32 s23, v248, 3
	s_waitcnt vmcnt(0)
	v_pk_add_f32 v[18:19], v[14:15], v[18:19]
	v_pk_add_f32 v[16:17], v[12:13], v[16:17]
	v_and_b32_sdwa v14, v19, v103 dst_sel:DWORD dst_unused:UNUSED_PAD src0_sel:WORD_1 src1_sel:DWORD
	v_and_b32_sdwa v13, v16, v103 dst_sel:DWORD dst_unused:UNUSED_PAD src0_sel:WORD_1 src1_sel:DWORD
	v_and_b32_sdwa v15, v17, v103 dst_sel:DWORD dst_unused:UNUSED_PAD src0_sel:WORD_1 src1_sel:DWORD
	v_and_b32_sdwa v12, v18, v103 dst_sel:DWORD dst_unused:UNUSED_PAD src0_sel:WORD_1 src1_sel:DWORD
	v_add3_u32 v24, v16, v13, s16
	v_add3_u32 v13, v19, v14, s16
	v_add3_u32 v14, v17, v15, s16
	v_add3_u32 v12, v18, v12, s16
	v_and_b32_e32 v13, 0xffff0000, v13
	v_and_b32_e32 v14, 0xffff0000, v14
	v_or_b32_sdwa v13, v13, v12 dst_sel:DWORD dst_unused:UNUSED_PAD src0_sel:DWORD src1_sel:WORD_1
	v_or_b32_sdwa v12, v14, v24 dst_sel:DWORD dst_unused:UNUSED_PAD src0_sel:DWORD src1_sel:WORD_1
	ds_write_b64 v180, v[12:13] offset:6144
	global_load_dwordx4 v[12:15], v[22:23], off offset:64
	v_pk_mul_f32 v[16:17], v[16:17], v[16:17]
	v_pk_mul_f32 v[18:19], v[18:19], v[18:19]
	v_add_f32_e32 v16, v16, v17
	v_add_f32_e32 v16, v16, v18
	v_add_f32_e32 v16, v16, v19
	s_waitcnt vmcnt(0)
	v_pk_add_f32 v[14:15], v[10:11], v[14:15]
	v_pk_add_f32 v[12:13], v[8:9], v[12:13]
	v_and_b32_sdwa v10, v15, v103 dst_sel:DWORD dst_unused:UNUSED_PAD src0_sel:WORD_1 src1_sel:DWORD
	v_and_b32_sdwa v9, v12, v103 dst_sel:DWORD dst_unused:UNUSED_PAD src0_sel:WORD_1 src1_sel:DWORD
	v_and_b32_sdwa v11, v13, v103 dst_sel:DWORD dst_unused:UNUSED_PAD src0_sel:WORD_1 src1_sel:DWORD
	v_and_b32_sdwa v8, v14, v103 dst_sel:DWORD dst_unused:UNUSED_PAD src0_sel:WORD_1 src1_sel:DWORD
	v_add3_u32 v24, v12, v9, s16
	v_add3_u32 v9, v15, v10, s16
	v_add3_u32 v10, v13, v11, s16
	v_add3_u32 v8, v14, v8, s16
	v_and_b32_e32 v9, 0xffff0000, v9
	v_and_b32_e32 v10, 0xffff0000, v10
	v_or_b32_sdwa v9, v9, v8 dst_sel:DWORD dst_unused:UNUSED_PAD src0_sel:DWORD src1_sel:WORD_1
	v_or_b32_sdwa v8, v10, v24 dst_sel:DWORD dst_unused:UNUSED_PAD src0_sel:DWORD src1_sel:WORD_1
	ds_write_b64 v181, v[8:9] offset:6144
	global_load_dwordx4 v[8:11], v[22:23], off offset:128
	v_pk_mul_f32 v[12:13], v[12:13], v[12:13]
	v_pk_mul_f32 v[14:15], v[14:15], v[14:15]
	v_add_f32_e32 v12, v12, v13
	v_add_f32_e32 v12, v12, v14
	v_add_f32_e32 v12, v12, v15
	v_add_f32_e32 v12, v16, v12
	s_waitcnt vmcnt(0)
	v_pk_add_f32 v[10:11], v[6:7], v[10:11]
	v_pk_add_f32 v[8:9], v[4:5], v[8:9]
	v_and_b32_sdwa v6, v11, v103 dst_sel:DWORD dst_unused:UNUSED_PAD src0_sel:WORD_1 src1_sel:DWORD
	v_and_b32_sdwa v5, v8, v103 dst_sel:DWORD dst_unused:UNUSED_PAD src0_sel:WORD_1 src1_sel:DWORD
	v_and_b32_sdwa v7, v9, v103 dst_sel:DWORD dst_unused:UNUSED_PAD src0_sel:WORD_1 src1_sel:DWORD
	v_and_b32_sdwa v4, v10, v103 dst_sel:DWORD dst_unused:UNUSED_PAD src0_sel:WORD_1 src1_sel:DWORD
	v_add3_u32 v24, v8, v5, s16
	v_add3_u32 v5, v11, v6, s16
	v_add3_u32 v6, v9, v7, s16
	v_add3_u32 v4, v10, v4, s16
	v_and_b32_e32 v5, 0xffff0000, v5
	v_and_b32_e32 v6, 0xffff0000, v6
	v_or_b32_sdwa v5, v5, v4 dst_sel:DWORD dst_unused:UNUSED_PAD src0_sel:DWORD src1_sel:WORD_1
	v_or_b32_sdwa v4, v6, v24 dst_sel:DWORD dst_unused:UNUSED_PAD src0_sel:DWORD src1_sel:WORD_1
	ds_write_b64 v182, v[4:5] offset:6144
	global_load_dwordx4 v[4:7], v[22:23], off offset:192
	v_pk_mul_f32 v[8:9], v[8:9], v[8:9]
	v_pk_mul_f32 v[10:11], v[10:11], v[10:11]
	v_add_f32_e32 v8, v8, v9
	v_add_f32_e32 v8, v8, v10
	v_add_f32_e32 v8, v8, v11
	v_add_f32_e32 v8, v12, v8
	s_waitcnt vmcnt(0)
	v_pk_add_f32 v[0:1], v[0:1], v[4:5]
	v_pk_add_f32 v[2:3], v[2:3], v[6:7]
	v_pk_mul_f32 v[6:7], v[0:1], v[0:1]
	v_pk_mul_f32 v[4:5], v[2:3], v[2:3]
	v_and_b32_sdwa v10, v0, v103 dst_sel:DWORD dst_unused:UNUSED_PAD src0_sel:WORD_1 src1_sel:DWORD
	v_add_f32_e32 v6, v6, v7
	v_add3_u32 v7, v0, v10, s16
	v_add_f32_e32 v0, v6, v4
	v_add_f32_e32 v0, v0, v5
	v_add_f32_e32 v0, v8, v0
	ds_bpermute_b32 v5, v53, v0
	v_and_b32_sdwa v4, v3, v103 dst_sel:DWORD dst_unused:UNUSED_PAD src0_sel:WORD_1 src1_sel:DWORD
	v_and_b32_sdwa v6, v1, v103 dst_sel:DWORD dst_unused:UNUSED_PAD src0_sel:WORD_1 src1_sel:DWORD
	v_add3_u32 v3, v3, v4, s16
	v_add3_u32 v4, v1, v6, s16
	s_waitcnt lgkmcnt(0)
	v_add_f32_e32 v0, v0, v5
	ds_bpermute_b32 v1, v52, v0
	v_and_b32_sdwa v9, v2, v103 dst_sel:DWORD dst_unused:UNUSED_PAD src0_sel:WORD_1 src1_sel:DWORD
	v_add3_u32 v2, v2, v9, s16
	v_and_b32_e32 v3, 0xffff0000, v3
	v_and_b32_e32 v4, 0xffff0000, v4
	v_or_b32_sdwa v3, v3, v2 dst_sel:DWORD dst_unused:UNUSED_PAD src0_sel:DWORD src1_sel:WORD_1
	v_or_b32_sdwa v2, v4, v7 dst_sel:DWORD dst_unused:UNUSED_PAD src0_sel:DWORD src1_sel:WORD_1
	ds_write_b64 v183, v[2:3] offset:6144
	s_waitcnt lgkmcnt(0)
	ds_read_b128 v[212:215], v184 offset:0
	ds_read_b128 v[216:219], v184 offset:1024
	ds_read_b128 v[220:223], v184 offset:2048
	ds_read_b128 v[224:227], v184 offset:3072
	ds_read_b128 v[228:231], v184 offset:4096
	ds_read_b128 v[232:235], v184 offset:5120
	ds_read_b128 v[236:239], v184 offset:6144
	ds_read_b128 v[240:243], v184 offset:7168
	s_waitcnt lgkmcnt(7)
	global_store_dwordx4 v185, v[212:215], s[98:99]
	v_add_u32_e32 v185, v185, v186
	s_waitcnt lgkmcnt(6)
	global_store_dwordx4 v185, v[216:219], s[98:99]
	v_add_u32_e32 v185, v185, v186
	s_waitcnt lgkmcnt(5)
	global_store_dwordx4 v185, v[220:223], s[98:99]
	v_add_u32_e32 v185, v185, v186
	s_waitcnt lgkmcnt(4)
	global_store_dwordx4 v185, v[224:227], s[98:99]
	v_add_u32_e32 v185, v185, v186
	s_waitcnt lgkmcnt(3)
	global_store_dwordx4 v185, v[228:231], s[98:99]
	v_add_u32_e32 v185, v185, v186
	s_waitcnt lgkmcnt(2)
	global_store_dwordx4 v185, v[232:235], s[98:99]
	v_add_u32_e32 v185, v185, v186
	s_waitcnt lgkmcnt(1)
	global_store_dwordx4 v185, v[236:239], s[98:99]
	v_add_u32_e32 v185, v185, v186
	s_waitcnt lgkmcnt(0)
	global_store_dwordx4 v185, v[240:243], s[98:99]
	s_barrier
	s_and_saveexec_b64 s[4:5], vcc
	s_cbranch_execz .LBB0_891
	s_waitcnt lgkmcnt(0)
	v_add_f32_e32 v0, v0, v1
	global_atomic_add_f32 v[48:49], v0, off offset:192
	s_branch .LBB0_891

; DEVI unsigned pack2(float a, float b) { return (unsigned)f2bf(a) | ((unsigned)f2bf(b) << 16); }
; template <bool RESB>
; DEVI void phase_resid(const Params& p, unsigned char* smem, const u16* A, const u16* Wt, const float* res, float* ssq) {
;     ...
; #pragma unroll
;     for (int mi = 0; mi < 4; ++mi) {
;       const int m = m0 + wm * 64 + 16 * mi + col;
;       float ss = 0.f;
; #pragma unroll
;       for (int ni = 0; ni < 4; ++ni) {
;         const int n = n0 + wn * 64 + 16 * ni + 4 * quad;
;         const f32x4 v = acc[ni][mi];
;         float4 r;
;         if (RESB) {
;           const uint2 rb = *(const uint2*)(p.hn + (size_t)m * LDA + n);
;           r.x = __uint_as_float(rb.x << 16); r.y = __uint_as_float(rb.x & 0xffff0000u);
;           r.z = __uint_as_float(rb.y << 16); r.w = __uint_as_float(rb.y & 0xffff0000u);
;         } else {
;           r = *(const float4*)(res + (size_t)m * D + n);
;         }
;         float4 hv;
;         hv.x = r.x + v[0]; hv.y = r.y + v[1]; hv.z = r.z + v[2]; hv.w = r.w + v[3];
;         ss += hv.x * hv.x + hv.y * hv.y + hv.z * hv.z + hv.w * hv.w;
;         uint2 pk; pk.x = pack2(hv.x, hv.y); pk.y = pack2(hv.z, hv.w);
;         *(uint2*)(p.hn + (size_t)m * LDA + n) = pk;
;       }
;       ss += __shfl_xor(ss, 16);
;       ss += __shfl_xor(ss, 32);
;       if (quad == 0) atomicAdd(ssq + m, ss);
;     }
.LBB0_1093:
	v_and_b32_e32 v200, 63, v210
	v_lshrrev_b32_e32 v201, 6, v210
	v_and_b32_e32 v202, 15, v200
	v_lshrrev_b32_e32 v203, 4, v200
	v_lshlrev_b32_e32 v204, 13, v201
	v_lshl_add_u32 v204, v202, 7, v204
	v_and_b32_e32 v205, 1, v203
	v_lshl_add_u32 v204, v205, 3, v204
	v_lshrrev_b32_e32 v205, 1, v203
	v_and_b32_e32 v206, 7, v202
	v_xor_b32_e32 v205, v205, v206
	v_xor_b32_e32 v207, 0, v205
	v_lshl_add_u32 v180, v207, 4, v204
	v_xor_b32_e32 v207, 2, v205
	v_lshl_add_u32 v181, v207, 4, v204
	v_xor_b32_e32 v207, 4, v205
	v_lshl_add_u32 v182, v207, 4, v204
	v_xor_b32_e32 v207, 6, v205
	v_lshl_add_u32 v183, v207, 4, v204
	v_lshrrev_b32_e32 v206, 3, v200
	v_and_b32_e32 v207, 7, v200
	v_lshlrev_b32_e32 v184, 13, v201
	v_lshl_add_u32 v184, v206, 7, v184
	v_lshl_add_u32 v184, v207, 4, v184
	v_xor_b32_e32 v207, v207, v206
	v_lshlrev_b32_e32 v207, 4, v207
	v_mul_lo_u32 v185, v206, s15
	v_add_u32_e32 v185, v185, v207
	v_mov_b32_e32 v186, s15
	v_lshlrev_b32_e32 v186, 3, v186
	v_ashrrev_i32_e32 v70, 1, v105
	v_and_b32_e32 v70, 0xffffffc0, v70
	v_add_u32_e32 v70, s18, v70
	v_readlane_b32 s20, v248, 0
	v_and_b32_e32 v64, 64, v105
	v_and_or_b32 v72, v105, 15, v70
	v_lshlrev_b32_e32 v70, 2, v104
	v_readlane_b32 s21, v248, 1
	v_or3_b32 v70, v70, v64, s17
	v_ashrrev_i32_e32 v71, 31, v70
	v_mov_b64_e32 v[74:75], s[20:21]
	v_mad_i64_i32 v[74:75], s[4:5], v72, s15, v[74:75]
	v_lshl_add_u64 v[74:75], v[70:71], 1, v[74:75]
	global_load_dwordx2 v[76:77], v[74:75], off
	global_load_dwordx2 v[78:79], v[74:75], off offset:32
	global_load_dwordx2 v[80:81], v[74:75], off offset:64
	global_load_dwordx2 v[84:85], v[74:75], off offset:96
	v_and_b32_e32 v73, 64, v102
	v_xor_b32_e32 v64, 16, v102
	v_mov_b32_e32 v82, v60
	v_mov_b32_e32 v60, v56
	v_mov_b32_e32 v56, v52
	v_add_u32_e32 v52, 64, v73
	v_xor_b32_e32 v86, 32, v102
	v_cmp_lt_i32_e64 s[4:5], v64, v52
	v_mov_b32_e32 v83, v62
	v_mov_b32_e32 v62, v61
	v_mov_b32_e32 v61, v58
	v_mov_b32_e32 v58, v57
	v_mov_b32_e32 v57, v54
	v_mov_b32_e32 v54, v53
	v_cndmask_b32_e64 v53, v102, v64, s[4:5]
	v_cmp_lt_i32_e64 s[4:5], v86, v52
	v_cmp_eq_u32_e32 vcc, 0, v104
	v_lshlrev_b32_e32 v53, 2, v53
	v_cndmask_b32_e64 v52, v102, v86, s[4:5]
	v_lshlrev_b32_e32 v52, 2, v52
	v_ashrrev_i32_e32 v73, 31, v72
	v_readlane_b32 s22, v248, 2
	v_readlane_b32 s23, v248, 3
	s_waitcnt vmcnt(3)
	v_lshlrev_b32_e32 v87, 16, v77
	v_lshlrev_b32_e32 v86, 16, v76
	v_and_b32_e32 v77, 0xffff0000, v77
	v_and_b32_e32 v76, 0xffff0000, v76
	s_waitcnt vmcnt(2)
	v_lshlrev_b32_e32 v89, 16, v79
	v_lshlrev_b32_e32 v88, 16, v78
	v_and_b32_e32 v79, 0xffff0000, v79
	v_and_b32_e32 v78, 0xffff0000, v78
	s_waitcnt vmcnt(1)
	v_lshlrev_b32_e32 v91, 16, v81
	v_lshlrev_b32_e32 v90, 16, v80
	v_and_b32_e32 v81, 0xffff0000, v81
	v_and_b32_e32 v80, 0xffff0000, v80
	v_pk_add_f32 v[62:63], v[62:63], v[76:77]
	v_pk_add_f32 v[58:59], v[58:59], v[78:79]
	v_pk_add_f32 v[54:55], v[54:55], v[80:81]
	v_pk_add_f32 v[82:83], v[82:83], v[86:87]
	v_pk_add_f32 v[60:61], v[60:61], v[88:89]
	v_pk_add_f32 v[56:57], v[56:57], v[90:91]
	v_and_b32_sdwa v93, v63, v103 dst_sel:DWORD dst_unused:UNUSED_PAD src0_sel:WORD_1 src1_sel:DWORD
	v_and_b32_sdwa v94, v62, v103 dst_sel:DWORD dst_unused:UNUSED_PAD src0_sel:WORD_1 src1_sel:DWORD
	v_and_b32_sdwa v97, v59, v103 dst_sel:DWORD dst_unused:UNUSED_PAD src0_sel:WORD_1 src1_sel:DWORD
	v_and_b32_sdwa v98, v58, v103 dst_sel:DWORD dst_unused:UNUSED_PAD src0_sel:WORD_1 src1_sel:DWORD
	v_and_b32_sdwa v101, v55, v103 dst_sel:DWORD dst_unused:UNUSED_PAD src0_sel:WORD_1 src1_sel:DWORD
	v_and_b32_sdwa v104, v54, v103 dst_sel:DWORD dst_unused:UNUSED_PAD src0_sel:WORD_1 src1_sel:DWORD
	v_pk_mul_f32 v[78:79], v[62:63], v[62:63]
	v_and_b32_sdwa v64, v83, v103 dst_sel:DWORD dst_unused:UNUSED_PAD src0_sel:WORD_1 src1_sel:DWORD
	v_and_b32_sdwa v92, v82, v103 dst_sel:DWORD dst_unused:UNUSED_PAD src0_sel:WORD_1 src1_sel:DWORD
	v_pk_mul_f32 v[86:87], v[58:59], v[58:59]
	v_and_b32_sdwa v95, v61, v103 dst_sel:DWORD dst_unused:UNUSED_PAD src0_sel:WORD_1 src1_sel:DWORD
	v_and_b32_sdwa v96, v60, v103 dst_sel:DWORD dst_unused:UNUSED_PAD src0_sel:WORD_1 src1_sel:DWORD
	v_pk_mul_f32 v[90:91], v[54:55], v[54:55]
	v_and_b32_sdwa v99, v57, v103 dst_sel:DWORD dst_unused:UNUSED_PAD src0_sel:WORD_1 src1_sel:DWORD
	v_and_b32_sdwa v100, v56, v103 dst_sel:DWORD dst_unused:UNUSED_PAD src0_sel:WORD_1 src1_sel:DWORD
	v_add3_u32 v63, v63, v93, s16
	v_add3_u32 v62, v62, v94, s16
	v_add3_u32 v59, v59, v97, s16
	v_add3_u32 v58, v58, v98, s16
	v_add3_u32 v55, v55, v101, s16
	v_add3_u32 v54, v54, v104, s16
	v_pk_mul_f32 v[76:77], v[82:83], v[82:83]
	v_pk_mul_f32 v[80:81], v[60:61], v[60:61]
	v_pk_mul_f32 v[88:89], v[56:57], v[56:57]
	v_add3_u32 v82, v82, v92, s16
	v_add3_u32 v64, v83, v64, s16
	v_add3_u32 v60, v60, v96, s16
	v_add3_u32 v61, v61, v95, s16
	v_add3_u32 v83, v56, v100, s16
	v_add3_u32 v92, v57, v99, s16
	v_and_b32_e32 v56, 0xffff0000, v63
	v_and_b32_e32 v62, 0xffff0000, v62
	v_and_b32_e32 v59, 0xffff0000, v59
	v_and_b32_e32 v58, 0xffff0000, v58
	v_and_b32_e32 v55, 0xffff0000, v55
	v_and_b32_e32 v54, 0xffff0000, v54
	v_or_b32_sdwa v57, v56, v64 dst_sel:DWORD dst_unused:UNUSED_PAD src0_sel:DWORD src1_sel:WORD_1
	v_or_b32_sdwa v56, v62, v82 dst_sel:DWORD dst_unused:UNUSED_PAD src0_sel:DWORD src1_sel:WORD_1
	v_or_b32_sdwa v59, v59, v61 dst_sel:DWORD dst_unused:UNUSED_PAD src0_sel:DWORD src1_sel:WORD_1
	v_or_b32_sdwa v58, v58, v60 dst_sel:DWORD dst_unused:UNUSED_PAD src0_sel:DWORD src1_sel:WORD_1
	v_or_b32_sdwa v55, v55, v92 dst_sel:DWORD dst_unused:UNUSED_PAD src0_sel:DWORD src1_sel:WORD_1
	v_or_b32_sdwa v54, v54, v83 dst_sel:DWORD dst_unused:UNUSED_PAD src0_sel:DWORD src1_sel:WORD_1
	v_readfirstlane_b32 s98, v74
	v_readfirstlane_b32 s99, v75
	ds_write_b64 v180, v[56:57]
	ds_write_b64 v181, v[58:59]
	ds_write_b64 v182, v[54:55]
	s_waitcnt vmcnt(0)
; DEVI unsigned pack2(float a, float b) { return (unsigned)f2bf(a) | ((unsigned)f2bf(b) << 16); }
; template <bool RESB>
; DEVI void phase_resid(const Params& p, unsigned char* smem, const u16* A, const u16* Wt, const float* res, float* ssq) {
;     ...
; #pragma unroll
;     for (int mi = 0; mi < 4; ++mi) {
;       const int m = m0 + wm * 64 + 16 * mi + col;
;       float ss = 0.f;
; #pragma unroll
;       for (int ni = 0; ni < 4; ++ni) {
;         const int n = n0 + wn * 64 + 16 * ni + 4 * quad;
;         const f32x4 v = acc[ni][mi];
;         float4 r;
;         if (RESB) {
;           const uint2 rb = *(const uint2*)(p.hn + (size_t)m * LDA + n);
;           r.x = __uint_as_float(rb.x << 16); r.y = __uint_as_float(rb.x & 0xffff0000u);
;           r.z = __uint_as_float(rb.y << 16); r.w = __uint_as_float(rb.y & 0xffff0000u);
;         } else {
;           r = *(const float4*)(res + (size_t)m * D + n);
;         }
;         float4 hv;
;         hv.x = r.x + v[0]; hv.y = r.y + v[1]; hv.z = r.z + v[2]; hv.w = r.w + v[3];
;         ss += hv.x * hv.x + hv.y * hv.y + hv.z * hv.z + hv.w * hv.w;
;         uint2 pk; pk.x = pack2(hv.x, hv.y); pk.y = pack2(hv.z, hv.w);
;         *(uint2*)(p.hn + (size_t)m * LDA + n) = pk;
;       }
;       ss += __shfl_xor(ss, 16);
;       ss += __shfl_xor(ss, 32);
;       if (quad == 0) atomicAdd(ssq + m, ss);
;     }
	v_lshlrev_b32_e32 v55, 16, v85
	v_lshlrev_b32_e32 v54, 16, v84
	v_mov_b32_e32 v58, v48
	v_mov_b32_e32 v59, v50
	v_pk_add_f32 v[54:55], v[58:59], v[54:55]
	v_add_f32_e32 v58, v80, v86
	v_add_f32_e32 v59, v76, v78
	v_and_b32_e32 v57, 0xffff0000, v85
	v_and_b32_e32 v56, 0xffff0000, v84
	v_mov_b32_e32 v50, v49
	v_add_f32_e32 v58, v58, v81
	v_add_f32_e32 v59, v59, v77
	v_pk_add_f32 v[48:49], v[50:51], v[56:57]
	v_add_f32_e32 v58, v87, v58
	v_add_f32_e32 v59, v79, v59
	v_pk_mul_f32 v[50:51], v[54:55], v[54:55]
	v_pk_mul_f32 v[56:57], v[48:49], v[48:49]
	v_add_f32_e32 v58, v59, v58
	v_add_f32_e32 v59, v88, v90
	v_add_f32_e32 v59, v59, v89
	v_add_f32_e32 v50, v50, v56
	v_add_f32_e32 v59, v91, v59
	v_add_f32_e32 v50, v50, v51
	v_add_f32_e32 v58, v58, v59
	v_add_f32_e32 v50, v57, v50
	v_add_f32_e32 v50, v58, v50
	ds_bpermute_b32 v57, v53, v50
	v_and_b32_sdwa v51, v55, v103 dst_sel:DWORD dst_unused:UNUSED_PAD src0_sel:WORD_1 src1_sel:DWORD
	v_and_b32_sdwa v56, v54, v103 dst_sel:DWORD dst_unused:UNUSED_PAD src0_sel:WORD_1 src1_sel:DWORD
	v_add3_u32 v55, v55, v51, s16
	v_and_b32_sdwa v51, v49, v103 dst_sel:DWORD dst_unused:UNUSED_PAD src0_sel:WORD_1 src1_sel:DWORD
	s_waitcnt lgkmcnt(0)
	v_add_f32_e32 v50, v50, v57
	v_add3_u32 v54, v54, v56, s16
	v_and_b32_sdwa v56, v48, v103 dst_sel:DWORD dst_unused:UNUSED_PAD src0_sel:WORD_1 src1_sel:DWORD
	v_add3_u32 v49, v49, v51, s16
	ds_bpermute_b32 v51, v52, v50
	v_add3_u32 v48, v48, v56, s16
	v_and_b32_e32 v49, 0xffff0000, v49
	v_and_b32_e32 v48, 0xffff0000, v48
	v_or_b32_sdwa v49, v49, v55 dst_sel:DWORD dst_unused:UNUSED_PAD src0_sel:DWORD src1_sel:WORD_1
	v_or_b32_sdwa v48, v48, v54 dst_sel:DWORD dst_unused:UNUSED_PAD src0_sel:DWORD src1_sel:WORD_1
	ds_write_b64 v183, v[48:49]
	v_lshl_add_u64 v[48:49], v[72:73], 2, s[50:51]
	s_and_saveexec_b64 s[4:5], vcc
	s_cbranch_execz .LBB0_1095
	s_waitcnt lgkmcnt(0)
	v_add_f32_e32 v50, v50, v51
	global_atomic_add_f32 v[48:49], v50, off
.LBB0_1095:
	s_or_b64 exec, exec, s[4:5]
	v_readlane_b32 s20, v248, 0
	v_readlane_b32 s21, v248, 1
	v_or_b32_e32 v54, 16, v72
	v_mov_b32_e32 v62, v44
	s_waitcnt lgkmcnt(0)
	v_mov_b64_e32 v[50:51], s[20:21]
	v_mad_i64_i32 v[50:51], s[4:5], v54, s15, v[50:51]
	v_lshl_add_u64 v[50:51], v[70:71], 1, v[50:51]
	global_load_dwordx2 v[54:55], v[50:51], off
	global_load_dwordx2 v[56:57], v[50:51], off offset:32
	global_load_dwordx2 v[58:59], v[50:51], off offset:64
	global_load_dwordx2 v[60:61], v[50:51], off offset:96
	v_mov_b32_e32 v63, v46
	v_mov_b32_e32 v46, v45
	v_mov_b32_e32 v44, v40
	v_mov_b32_e32 v45, v42
	v_mov_b32_e32 v42, v41
	v_mov_b32_e32 v40, v36
	v_mov_b32_e32 v41, v38
	v_mov_b32_e32 v38, v37
	v_mov_b32_e32 v36, v32
	v_mov_b32_e32 v37, v34
	v_mov_b32_e32 v34, v33
	v_readlane_b32 s22, v248, 2
	v_readlane_b32 s23, v248, 3
	s_waitcnt vmcnt(3)
	v_lshlrev_b32_e32 v33, 16, v55
	v_lshlrev_b32_e32 v32, 16, v54
	v_and_b32_e32 v55, 0xffff0000, v55
	v_and_b32_e32 v54, 0xffff0000, v54
	s_waitcnt vmcnt(1)
	v_lshlrev_b32_e32 v77, 16, v59
	v_lshlrev_b32_e32 v76, 16, v58
	v_and_b32_e32 v59, 0xffff0000, v59
	v_and_b32_e32 v58, 0xffff0000, v58
	v_lshlrev_b32_e32 v75, 16, v57
	v_lshlrev_b32_e32 v74, 16, v56
	v_and_b32_e32 v57, 0xffff0000, v57
	v_and_b32_e32 v56, 0xffff0000, v56
	v_pk_add_f32 v[46:47], v[46:47], v[54:55]
	v_pk_add_f32 v[38:39], v[38:39], v[58:59]
	v_pk_add_f32 v[32:33], v[62:63], v[32:33]
	v_pk_add_f32 v[42:43], v[42:43], v[56:57]
	v_pk_add_f32 v[40:41], v[40:41], v[76:77]
	v_and_b32_sdwa v76, v47, v103 dst_sel:DWORD dst_unused:UNUSED_PAD src0_sel:WORD_1 src1_sel:DWORD
	v_and_b32_sdwa v77, v46, v103 dst_sel:DWORD dst_unused:UNUSED_PAD src0_sel:WORD_1 src1_sel:DWORD
	v_and_b32_sdwa v84, v39, v103 dst_sel:DWORD dst_unused:UNUSED_PAD src0_sel:WORD_1 src1_sel:DWORD
	v_and_b32_sdwa v85, v38, v103 dst_sel:DWORD dst_unused:UNUSED_PAD src0_sel:WORD_1 src1_sel:DWORD
	s_waitcnt vmcnt(0)
	v_lshlrev_b32_e32 v79, 16, v61
	v_lshlrev_b32_e32 v78, 16, v60
	v_and_b32_e32 v61, 0xffff0000, v61
	v_and_b32_e32 v60, 0xffff0000, v60
	v_pk_add_f32 v[44:45], v[44:45], v[74:75]
	v_pk_mul_f32 v[56:57], v[46:47], v[46:47]
	v_and_b32_sdwa v64, v33, v103 dst_sel:DWORD dst_unused:UNUSED_PAD src0_sel:WORD_1 src1_sel:DWORD
	v_and_b32_sdwa v73, v32, v103 dst_sel:DWORD dst_unused:UNUSED_PAD src0_sel:WORD_1 src1_sel:DWORD
	v_and_b32_sdwa v80, v43, v103 dst_sel:DWORD dst_unused:UNUSED_PAD src0_sel:WORD_1 src1_sel:DWORD
	v_and_b32_sdwa v81, v42, v103 dst_sel:DWORD dst_unused:UNUSED_PAD src0_sel:WORD_1 src1_sel:DWORD
	v_pk_mul_f32 v[74:75], v[38:39], v[38:39]
	v_and_b32_sdwa v82, v41, v103 dst_sel:DWORD dst_unused:UNUSED_PAD src0_sel:WORD_1 src1_sel:DWORD
	v_and_b32_sdwa v83, v40, v103 dst_sel:DWORD dst_unused:UNUSED_PAD src0_sel:WORD_1 src1_sel:DWORD
	v_add3_u32 v47, v47, v76, s16
	v_add3_u32 v46, v46, v77, s16
	v_add3_u32 v39, v39, v84, s16
	v_add3_u32 v38, v38, v85, s16
	v_pk_add_f32 v[36:37], v[36:37], v[78:79]
	v_pk_add_f32 v[34:35], v[34:35], v[60:61]
	v_pk_mul_f32 v[54:55], v[32:33], v[32:33]
	v_pk_mul_f32 v[60:61], v[42:43], v[42:43]
	v_and_b32_sdwa v78, v45, v103 dst_sel:DWORD dst_unused:UNUSED_PAD src0_sel:WORD_1 src1_sel:DWORD
	v_and_b32_sdwa v79, v44, v103 dst_sel:DWORD dst_unused:UNUSED_PAD src0_sel:WORD_1 src1_sel:DWORD
	v_pk_mul_f32 v[62:63], v[40:41], v[40:41]
	v_add3_u32 v32, v32, v73, s16
	v_add3_u32 v33, v33, v64, s16
	v_add3_u32 v43, v43, v80, s16
	v_add3_u32 v42, v42, v81, s16
	v_add3_u32 v40, v40, v83, s16
	v_add3_u32 v41, v41, v82, s16
	v_and_b32_e32 v47, 0xffff0000, v47
	v_and_b32_e32 v46, 0xffff0000, v46
	v_and_b32_e32 v64, 0xffff0000, v39
	v_and_b32_e32 v73, 0xffff0000, v38
	v_pk_mul_f32 v[58:59], v[44:45], v[44:45]
	v_add3_u32 v44, v44, v79, s16
; DEVI unsigned pack2(float a, float b) { return (unsigned)f2bf(a) | ((unsigned)f2bf(b) << 16); }
; template <bool RESB>
; DEVI void phase_resid(const Params& p, unsigned char* smem, const u16* A, const u16* Wt, const float* res, float* ssq) {
;     ...
; #pragma unroll
;     for (int mi = 0; mi < 4; ++mi) {
;       const int m = m0 + wm * 64 + 16 * mi + col;
;       float ss = 0.f;
; #pragma unroll
;       for (int ni = 0; ni < 4; ++ni) {
;         const int n = n0 + wn * 64 + 16 * ni + 4 * quad;
;         const f32x4 v = acc[ni][mi];
;         float4 r;
;         if (RESB) {
;           const uint2 rb = *(const uint2*)(p.hn + (size_t)m * LDA + n);
;           r.x = __uint_as_float(rb.x << 16); r.y = __uint_as_float(rb.x & 0xffff0000u);
;           r.z = __uint_as_float(rb.y << 16); r.w = __uint_as_float(rb.y & 0xffff0000u);
;         } else {
;           r = *(const float4*)(res + (size_t)m * D + n);
;         }
;         float4 hv;
;         hv.x = r.x + v[0]; hv.y = r.y + v[1]; hv.z = r.z + v[2]; hv.w = r.w + v[3];
;         ss += hv.x * hv.x + hv.y * hv.y + hv.z * hv.z + hv.w * hv.w;
;         uint2 pk; pk.x = pack2(hv.x, hv.y); pk.y = pack2(hv.z, hv.w);
;         *(uint2*)(p.hn + (size_t)m * LDA + n) = pk;
;       }
;       ss += __shfl_xor(ss, 16);
;       ss += __shfl_xor(ss, 32);
;       if (quad == 0) atomicAdd(ssq + m, ss);
;     }
	v_add3_u32 v45, v45, v78, s16
	v_and_b32_e32 v43, 0xffff0000, v43
	v_and_b32_e32 v42, 0xffff0000, v42
	v_or_b32_sdwa v33, v47, v33 dst_sel:DWORD dst_unused:UNUSED_PAD src0_sel:DWORD src1_sel:WORD_1
	v_or_b32_sdwa v32, v46, v32 dst_sel:DWORD dst_unused:UNUSED_PAD src0_sel:DWORD src1_sel:WORD_1
	v_or_b32_sdwa v41, v64, v41 dst_sel:DWORD dst_unused:UNUSED_PAD src0_sel:DWORD src1_sel:WORD_1
	v_or_b32_sdwa v40, v73, v40 dst_sel:DWORD dst_unused:UNUSED_PAD src0_sel:DWORD src1_sel:WORD_1
	v_or_b32_sdwa v39, v43, v45 dst_sel:DWORD dst_unused:UNUSED_PAD src0_sel:DWORD src1_sel:WORD_1
	v_or_b32_sdwa v38, v42, v44 dst_sel:DWORD dst_unused:UNUSED_PAD src0_sel:DWORD src1_sel:WORD_1
	ds_write_b64 v180, v[32:33] offset:2048
	ds_write_b64 v181, v[38:39] offset:2048
	ds_write_b64 v182, v[40:41] offset:2048
	v_add_f32_e32 v40, v58, v60
	v_add_f32_e32 v41, v54, v56
	v_add_f32_e32 v40, v40, v59
	v_add_f32_e32 v41, v41, v55
	v_add_f32_e32 v40, v61, v40
	v_add_f32_e32 v41, v57, v41
	v_pk_mul_f32 v[32:33], v[36:37], v[36:37]
	v_pk_mul_f32 v[38:39], v[34:35], v[34:35]
	v_add_f32_e32 v40, v41, v40
	v_add_f32_e32 v41, v62, v74
	v_add_f32_e32 v41, v41, v63
	v_add_f32_e32 v32, v32, v38
	v_add_f32_e32 v41, v75, v41
	v_add_f32_e32 v32, v32, v33
	v_add_f32_e32 v40, v40, v41
	v_add_f32_e32 v32, v39, v32
	v_add_f32_e32 v32, v40, v32
	v_and_b32_sdwa v38, v36, v103 dst_sel:DWORD dst_unused:UNUSED_PAD src0_sel:WORD_1 src1_sel:DWORD
	v_add3_u32 v36, v36, v38, s16
	ds_bpermute_b32 v38, v53, v32
	v_and_b32_sdwa v33, v37, v103 dst_sel:DWORD dst_unused:UNUSED_PAD src0_sel:WORD_1 src1_sel:DWORD
	v_add3_u32 v37, v37, v33, s16
	v_and_b32_sdwa v33, v35, v103 dst_sel:DWORD dst_unused:UNUSED_PAD src0_sel:WORD_1 src1_sel:DWORD
	v_add3_u32 v33, v35, v33, s16
	s_waitcnt lgkmcnt(0)
	v_add_f32_e32 v32, v32, v38
	v_and_b32_e32 v35, 0xffff0000, v33
	ds_bpermute_b32 v33, v52, v32
	v_and_b32_sdwa v39, v34, v103 dst_sel:DWORD dst_unused:UNUSED_PAD src0_sel:WORD_1 src1_sel:DWORD
	v_add3_u32 v34, v34, v39, s16
	v_and_b32_e32 v34, 0xffff0000, v34
	v_or_b32_sdwa v35, v35, v37 dst_sel:DWORD dst_unused:UNUSED_PAD src0_sel:DWORD src1_sel:WORD_1
	v_or_b32_sdwa v34, v34, v36 dst_sel:DWORD dst_unused:UNUSED_PAD src0_sel:DWORD src1_sel:WORD_1
	ds_write_b64 v183, v[34:35] offset:2048
	s_and_saveexec_b64 s[4:5], vcc
	s_cbranch_execz .LBB0_1097
	s_waitcnt lgkmcnt(0)
	v_add_f32_e32 v32, v32, v33
	global_atomic_add_f32 v[48:49], v32, off offset:64
.LBB0_1097:
	s_or_b64 exec, exec, s[4:5]
	v_readlane_b32 s20, v248, 0
	v_readlane_b32 s21, v248, 1
	v_or_b32_e32 v34, 32, v72
	v_mov_b32_e32 v42, v28
	s_waitcnt lgkmcnt(0)
	v_mov_b64_e32 v[32:33], s[20:21]
	v_mad_i64_i32 v[32:33], s[4:5], v34, s15, v[32:33]
	v_lshl_add_u64 v[32:33], v[70:71], 1, v[32:33]
	global_load_dwordx2 v[34:35], v[32:33], off
	global_load_dwordx2 v[36:37], v[32:33], off offset:32
	global_load_dwordx2 v[38:39], v[32:33], off offset:64
	global_load_dwordx2 v[40:41], v[32:33], off offset:96
	v_mov_b32_e32 v43, v30
	v_mov_b32_e32 v30, v29
	v_mov_b32_e32 v28, v24
	v_mov_b32_e32 v29, v26
	v_mov_b32_e32 v26, v25
	v_mov_b32_e32 v24, v20
	v_mov_b32_e32 v25, v22
	v_mov_b32_e32 v22, v21
	v_mov_b32_e32 v20, v16
	v_mov_b32_e32 v21, v18
	v_mov_b32_e32 v18, v17
	v_readlane_b32 s22, v248, 2
	v_readlane_b32 s23, v248, 3
	s_waitcnt vmcnt(3)
	v_lshlrev_b32_e32 v17, 16, v35
	v_lshlrev_b32_e32 v16, 16, v34
	v_and_b32_e32 v35, 0xffff0000, v35
	v_and_b32_e32 v34, 0xffff0000, v34
	s_waitcnt vmcnt(1)
	v_lshlrev_b32_e32 v47, 16, v39
	v_lshlrev_b32_e32 v46, 16, v38
	v_and_b32_e32 v39, 0xffff0000, v39
	v_and_b32_e32 v38, 0xffff0000, v38
	v_lshlrev_b32_e32 v45, 16, v37
	v_lshlrev_b32_e32 v44, 16, v36
	v_and_b32_e32 v37, 0xffff0000, v37
	v_and_b32_e32 v36, 0xffff0000, v36
	s_waitcnt vmcnt(0)
	v_lshlrev_b32_e32 v51, 16, v41
	v_lshlrev_b32_e32 v50, 16, v40
	v_pk_add_f32 v[30:31], v[30:31], v[34:35]
	v_pk_add_f32 v[22:23], v[22:23], v[38:39]
	v_pk_add_f32 v[16:17], v[42:43], v[16:17]
	v_pk_add_f32 v[26:27], v[26:27], v[36:37]
	v_pk_add_f32 v[24:25], v[24:25], v[46:47]
	v_pk_add_f32 v[20:21], v[20:21], v[50:51]
	v_and_b32_sdwa v50, v31, v103 dst_sel:DWORD dst_unused:UNUSED_PAD src0_sel:WORD_1 src1_sel:DWORD
	v_and_b32_sdwa v51, v30, v103 dst_sel:DWORD dst_unused:UNUSED_PAD src0_sel:WORD_1 src1_sel:DWORD
	v_and_b32_sdwa v60, v23, v103 dst_sel:DWORD dst_unused:UNUSED_PAD src0_sel:WORD_1 src1_sel:DWORD
	v_and_b32_sdwa v61, v22, v103 dst_sel:DWORD dst_unused:UNUSED_PAD src0_sel:WORD_1 src1_sel:DWORD
	v_and_b32_e32 v41, 0xffff0000, v41
	v_and_b32_e32 v40, 0xffff0000, v40
	v_pk_add_f32 v[28:29], v[28:29], v[44:45]
	v_pk_mul_f32 v[36:37], v[30:31], v[30:31]
	v_and_b32_sdwa v46, v17, v103 dst_sel:DWORD dst_unused:UNUSED_PAD src0_sel:WORD_1 src1_sel:DWORD
	v_and_b32_sdwa v47, v16, v103 dst_sel:DWORD dst_unused:UNUSED_PAD src0_sel:WORD_1 src1_sel:DWORD
	v_and_b32_sdwa v56, v27, v103 dst_sel:DWORD dst_unused:UNUSED_PAD src0_sel:WORD_1 src1_sel:DWORD
	v_and_b32_sdwa v57, v26, v103 dst_sel:DWORD dst_unused:UNUSED_PAD src0_sel:WORD_1 src1_sel:DWORD
	v_pk_mul_f32 v[44:45], v[22:23], v[22:23]
	v_and_b32_sdwa v58, v25, v103 dst_sel:DWORD dst_unused:UNUSED_PAD src0_sel:WORD_1 src1_sel:DWORD
	v_and_b32_sdwa v59, v24, v103 dst_sel:DWORD dst_unused:UNUSED_PAD src0_sel:WORD_1 src1_sel:DWORD
	v_add3_u32 v31, v31, v50, s16
	v_add3_u32 v30, v30, v51, s16
	v_add3_u32 v23, v23, v60, s16
	v_add3_u32 v22, v22, v61, s16
	v_pk_add_f32 v[18:19], v[18:19], v[40:41]
	v_pk_mul_f32 v[34:35], v[16:17], v[16:17]
	v_pk_mul_f32 v[40:41], v[26:27], v[26:27]
	v_and_b32_sdwa v54, v29, v103 dst_sel:DWORD dst_unused:UNUSED_PAD src0_sel:WORD_1 src1_sel:DWORD
	v_and_b32_sdwa v55, v28, v103 dst_sel:DWORD dst_unused:UNUSED_PAD src0_sel:WORD_1 src1_sel:DWORD
; DEVI unsigned pack2(float a, float b) { return (unsigned)f2bf(a) | ((unsigned)f2bf(b) << 16); }
; template <bool RESB>
; DEVI void phase_resid(const Params& p, unsigned char* smem, const u16* A, const u16* Wt, const float* res, float* ssq) {
;     ...
; #pragma unroll
;     for (int mi = 0; mi < 4; ++mi) {
;       const int m = m0 + wm * 64 + 16 * mi + col;
;       float ss = 0.f;
; #pragma unroll
;       for (int ni = 0; ni < 4; ++ni) {
;         const int n = n0 + wn * 64 + 16 * ni + 4 * quad;
;         const f32x4 v = acc[ni][mi];
;         float4 r;
;         if (RESB) {
;           const uint2 rb = *(const uint2*)(p.hn + (size_t)m * LDA + n);
;           r.x = __uint_as_float(rb.x << 16); r.y = __uint_as_float(rb.x & 0xffff0000u);
;           r.z = __uint_as_float(rb.y << 16); r.w = __uint_as_float(rb.y & 0xffff0000u);
;         } else {
;           r = *(const float4*)(res + (size_t)m * D + n);
;         }
;         float4 hv;
;         hv.x = r.x + v[0]; hv.y = r.y + v[1]; hv.z = r.z + v[2]; hv.w = r.w + v[3];
;         ss += hv.x * hv.x + hv.y * hv.y + hv.z * hv.z + hv.w * hv.w;
;         uint2 pk; pk.x = pack2(hv.x, hv.y); pk.y = pack2(hv.z, hv.w);
;         *(uint2*)(p.hn + (size_t)m * LDA + n) = pk;
;       }
;       ss += __shfl_xor(ss, 16);
;       ss += __shfl_xor(ss, 32);
;       if (quad == 0) atomicAdd(ssq + m, ss);
;     }
	v_pk_mul_f32 v[42:43], v[24:25], v[24:25]
	v_add3_u32 v16, v16, v47, s16
	v_add3_u32 v17, v17, v46, s16
	v_add3_u32 v27, v27, v56, s16
	v_add3_u32 v26, v26, v57, s16
	v_add3_u32 v24, v24, v59, s16
	v_add3_u32 v25, v25, v58, s16
	v_and_b32_e32 v31, 0xffff0000, v31
	v_and_b32_e32 v30, 0xffff0000, v30
	v_and_b32_e32 v46, 0xffff0000, v23
	v_and_b32_e32 v47, 0xffff0000, v22
	v_pk_mul_f32 v[38:39], v[28:29], v[28:29]
	v_add3_u32 v28, v28, v55, s16
	v_add3_u32 v29, v29, v54, s16
	v_and_b32_e32 v27, 0xffff0000, v27
	v_and_b32_e32 v26, 0xffff0000, v26
	v_or_b32_sdwa v17, v31, v17 dst_sel:DWORD dst_unused:UNUSED_PAD src0_sel:DWORD src1_sel:WORD_1
	v_or_b32_sdwa v16, v30, v16 dst_sel:DWORD dst_unused:UNUSED_PAD src0_sel:DWORD src1_sel:WORD_1
	v_or_b32_sdwa v25, v46, v25 dst_sel:DWORD dst_unused:UNUSED_PAD src0_sel:DWORD src1_sel:WORD_1
	v_or_b32_sdwa v24, v47, v24 dst_sel:DWORD dst_unused:UNUSED_PAD src0_sel:DWORD src1_sel:WORD_1
	v_or_b32_sdwa v23, v27, v29 dst_sel:DWORD dst_unused:UNUSED_PAD src0_sel:DWORD src1_sel:WORD_1
	v_or_b32_sdwa v22, v26, v28 dst_sel:DWORD dst_unused:UNUSED_PAD src0_sel:DWORD src1_sel:WORD_1
	ds_write_b64 v180, v[16:17] offset:4096
	ds_write_b64 v181, v[22:23] offset:4096
	ds_write_b64 v182, v[24:25] offset:4096
	v_add_f32_e32 v24, v38, v40
	v_add_f32_e32 v25, v34, v36
	v_add_f32_e32 v24, v24, v39
	v_add_f32_e32 v25, v25, v35
	v_add_f32_e32 v24, v41, v24
	v_add_f32_e32 v25, v37, v25
	v_pk_mul_f32 v[16:17], v[20:21], v[20:21]
	v_pk_mul_f32 v[22:23], v[18:19], v[18:19]
	v_add_f32_e32 v24, v25, v24
	v_add_f32_e32 v25, v42, v44
	v_add_f32_e32 v25, v25, v43
	v_add_f32_e32 v16, v16, v22
	v_add_f32_e32 v25, v45, v25
	v_add_f32_e32 v16, v16, v17
	v_add_f32_e32 v24, v24, v25
	v_add_f32_e32 v16, v23, v16
	v_add_f32_e32 v16, v24, v16
	v_and_b32_sdwa v22, v20, v103 dst_sel:DWORD dst_unused:UNUSED_PAD src0_sel:WORD_1 src1_sel:DWORD
	v_add3_u32 v20, v20, v22, s16
	ds_bpermute_b32 v22, v53, v16
	v_and_b32_sdwa v17, v21, v103 dst_sel:DWORD dst_unused:UNUSED_PAD src0_sel:WORD_1 src1_sel:DWORD
	v_add3_u32 v21, v21, v17, s16
	v_and_b32_sdwa v17, v19, v103 dst_sel:DWORD dst_unused:UNUSED_PAD src0_sel:WORD_1 src1_sel:DWORD
	v_add3_u32 v17, v19, v17, s16
	s_waitcnt lgkmcnt(0)
	v_add_f32_e32 v16, v16, v22
	v_and_b32_e32 v19, 0xffff0000, v17
	ds_bpermute_b32 v17, v52, v16
	v_and_b32_sdwa v23, v18, v103 dst_sel:DWORD dst_unused:UNUSED_PAD src0_sel:WORD_1 src1_sel:DWORD
	v_add3_u32 v18, v18, v23, s16
	v_and_b32_e32 v18, 0xffff0000, v18
	v_or_b32_sdwa v19, v19, v21 dst_sel:DWORD dst_unused:UNUSED_PAD src0_sel:DWORD src1_sel:WORD_1
	v_or_b32_sdwa v18, v18, v20 dst_sel:DWORD dst_unused:UNUSED_PAD src0_sel:DWORD src1_sel:WORD_1
	ds_write_b64 v183, v[18:19] offset:4096
	s_and_saveexec_b64 s[4:5], vcc
	s_cbranch_execz .LBB0_1099
	s_waitcnt lgkmcnt(0)
	v_add_f32_e32 v16, v16, v17
	global_atomic_add_f32 v[48:49], v16, off offset:128
.LBB0_1099:
	s_or_b64 exec, exec, s[4:5]
	v_readlane_b32 s20, v248, 0
	v_readlane_b32 s21, v248, 1
	v_or_b32_e32 v18, 48, v72
	v_mov_b32_e32 v26, v12
	s_waitcnt lgkmcnt(0)
	v_mov_b64_e32 v[16:17], s[20:21]
	v_mad_i64_i32 v[16:17], s[4:5], v18, s15, v[16:17]
	v_lshl_add_u64 v[16:17], v[70:71], 1, v[16:17]
	global_load_dwordx2 v[18:19], v[16:17], off
	global_load_dwordx2 v[20:21], v[16:17], off offset:32
	global_load_dwordx2 v[22:23], v[16:17], off offset:64
	global_load_dwordx2 v[24:25], v[16:17], off offset:96
	v_mov_b32_e32 v27, v14
	v_mov_b32_e32 v14, v13
	v_mov_b32_e32 v12, v8
	v_mov_b32_e32 v13, v10
	v_mov_b32_e32 v10, v9
	v_mov_b32_e32 v8, v4
	v_mov_b32_e32 v9, v6
	v_mov_b32_e32 v6, v5
	v_mov_b32_e32 v4, v0
	v_mov_b32_e32 v5, v2
	v_mov_b32_e32 v2, v1
	v_readlane_b32 s22, v248, 2
	v_readlane_b32 s23, v248, 3
	s_waitcnt vmcnt(3)
	v_lshlrev_b32_e32 v1, 16, v19
	v_lshlrev_b32_e32 v0, 16, v18
	v_and_b32_e32 v19, 0xffff0000, v19
	v_and_b32_e32 v18, 0xffff0000, v18
	s_waitcnt vmcnt(1)
	v_lshlrev_b32_e32 v31, 16, v23
	v_lshlrev_b32_e32 v30, 16, v22
	v_and_b32_e32 v23, 0xffff0000, v23
	v_and_b32_e32 v22, 0xffff0000, v22
	v_lshlrev_b32_e32 v29, 16, v21
	v_lshlrev_b32_e32 v28, 16, v20
	v_and_b32_e32 v21, 0xffff0000, v21
	v_and_b32_e32 v20, 0xffff0000, v20
	s_waitcnt vmcnt(0)
; DEVI unsigned pack2(float a, float b) { return (unsigned)f2bf(a) | ((unsigned)f2bf(b) << 16); }
; template <bool RESB>
; DEVI void phase_resid(const Params& p, unsigned char* smem, const u16* A, const u16* Wt, const float* res, float* ssq) {
;     ...
; #pragma unroll
;     for (int mi = 0; mi < 4; ++mi) {
;       const int m = m0 + wm * 64 + 16 * mi + col;
;       float ss = 0.f;
; #pragma unroll
;       for (int ni = 0; ni < 4; ++ni) {
;         const int n = n0 + wn * 64 + 16 * ni + 4 * quad;
;         const f32x4 v = acc[ni][mi];
;         float4 r;
;         if (RESB) {
;           const uint2 rb = *(const uint2*)(p.hn + (size_t)m * LDA + n);
;           r.x = __uint_as_float(rb.x << 16); r.y = __uint_as_float(rb.x & 0xffff0000u);
;           r.z = __uint_as_float(rb.y << 16); r.w = __uint_as_float(rb.y & 0xffff0000u);
;         } else {
;           r = *(const float4*)(res + (size_t)m * D + n);
;         }
;         float4 hv;
;         hv.x = r.x + v[0]; hv.y = r.y + v[1]; hv.z = r.z + v[2]; hv.w = r.w + v[3];
;         ss += hv.x * hv.x + hv.y * hv.y + hv.z * hv.z + hv.w * hv.w;
;         uint2 pk; pk.x = pack2(hv.x, hv.y); pk.y = pack2(hv.z, hv.w);
;         *(uint2*)(p.hn + (size_t)m * LDA + n) = pk;
;       }
;       ss += __shfl_xor(ss, 16);
;       ss += __shfl_xor(ss, 32);
;       if (quad == 0) atomicAdd(ssq + m, ss);
;     }
	v_lshlrev_b32_e32 v33, 16, v25
	v_lshlrev_b32_e32 v32, 16, v24
	v_pk_add_f32 v[14:15], v[14:15], v[18:19]
	v_pk_add_f32 v[6:7], v[6:7], v[22:23]
	v_pk_add_f32 v[0:1], v[26:27], v[0:1]
	v_pk_add_f32 v[10:11], v[10:11], v[20:21]
	v_pk_add_f32 v[8:9], v[8:9], v[30:31]
	v_pk_add_f32 v[4:5], v[4:5], v[32:33]
	v_and_b32_sdwa v32, v15, v103 dst_sel:DWORD dst_unused:UNUSED_PAD src0_sel:WORD_1 src1_sel:DWORD
	v_and_b32_sdwa v33, v14, v103 dst_sel:DWORD dst_unused:UNUSED_PAD src0_sel:WORD_1 src1_sel:DWORD
	v_and_b32_sdwa v40, v7, v103 dst_sel:DWORD dst_unused:UNUSED_PAD src0_sel:WORD_1 src1_sel:DWORD
	v_and_b32_sdwa v41, v6, v103 dst_sel:DWORD dst_unused:UNUSED_PAD src0_sel:WORD_1 src1_sel:DWORD
	v_and_b32_e32 v25, 0xffff0000, v25
	v_and_b32_e32 v24, 0xffff0000, v24
	v_pk_add_f32 v[12:13], v[12:13], v[28:29]
	v_pk_mul_f32 v[20:21], v[14:15], v[14:15]
	v_and_b32_sdwa v30, v1, v103 dst_sel:DWORD dst_unused:UNUSED_PAD src0_sel:WORD_1 src1_sel:DWORD
	v_and_b32_sdwa v31, v0, v103 dst_sel:DWORD dst_unused:UNUSED_PAD src0_sel:WORD_1 src1_sel:DWORD
	v_and_b32_sdwa v36, v11, v103 dst_sel:DWORD dst_unused:UNUSED_PAD src0_sel:WORD_1 src1_sel:DWORD
	v_and_b32_sdwa v37, v10, v103 dst_sel:DWORD dst_unused:UNUSED_PAD src0_sel:WORD_1 src1_sel:DWORD
	v_pk_mul_f32 v[28:29], v[6:7], v[6:7]
	v_and_b32_sdwa v38, v9, v103 dst_sel:DWORD dst_unused:UNUSED_PAD src0_sel:WORD_1 src1_sel:DWORD
	v_and_b32_sdwa v39, v8, v103 dst_sel:DWORD dst_unused:UNUSED_PAD src0_sel:WORD_1 src1_sel:DWORD
	v_add3_u32 v15, v15, v32, s16
	v_add3_u32 v14, v14, v33, s16
	v_add3_u32 v7, v7, v40, s16
	v_add3_u32 v6, v6, v41, s16
	v_pk_add_f32 v[2:3], v[2:3], v[24:25]
	v_pk_mul_f32 v[18:19], v[0:1], v[0:1]
	v_pk_mul_f32 v[24:25], v[10:11], v[10:11]
	v_and_b32_sdwa v34, v13, v103 dst_sel:DWORD dst_unused:UNUSED_PAD src0_sel:WORD_1 src1_sel:DWORD
	v_and_b32_sdwa v35, v12, v103 dst_sel:DWORD dst_unused:UNUSED_PAD src0_sel:WORD_1 src1_sel:DWORD
	v_pk_mul_f32 v[26:27], v[8:9], v[8:9]
	v_add3_u32 v0, v0, v31, s16
	v_add3_u32 v1, v1, v30, s16
	v_add3_u32 v11, v11, v36, s16
	v_add3_u32 v10, v10, v37, s16
	v_add3_u32 v8, v8, v39, s16
	v_add3_u32 v9, v9, v38, s16
	v_and_b32_e32 v15, 0xffff0000, v15
	v_and_b32_e32 v14, 0xffff0000, v14
	v_and_b32_e32 v30, 0xffff0000, v7
	v_and_b32_e32 v31, 0xffff0000, v6
	v_pk_mul_f32 v[22:23], v[12:13], v[12:13]
	v_add3_u32 v12, v12, v35, s16
	v_add3_u32 v13, v13, v34, s16
	v_and_b32_e32 v11, 0xffff0000, v11
	v_and_b32_e32 v10, 0xffff0000, v10
	v_or_b32_sdwa v1, v15, v1 dst_sel:DWORD dst_unused:UNUSED_PAD src0_sel:DWORD src1_sel:WORD_1
	v_or_b32_sdwa v0, v14, v0 dst_sel:DWORD dst_unused:UNUSED_PAD src0_sel:DWORD src1_sel:WORD_1
	v_or_b32_sdwa v9, v30, v9 dst_sel:DWORD dst_unused:UNUSED_PAD src0_sel:DWORD src1_sel:WORD_1
	v_or_b32_sdwa v8, v31, v8 dst_sel:DWORD dst_unused:UNUSED_PAD src0_sel:DWORD src1_sel:WORD_1
	v_or_b32_sdwa v7, v11, v13 dst_sel:DWORD dst_unused:UNUSED_PAD src0_sel:DWORD src1_sel:WORD_1
	v_or_b32_sdwa v6, v10, v12 dst_sel:DWORD dst_unused:UNUSED_PAD src0_sel:DWORD src1_sel:WORD_1
	ds_write_b64 v180, v[0:1] offset:6144
	ds_write_b64 v181, v[6:7] offset:6144
	ds_write_b64 v182, v[8:9] offset:6144
	v_add_f32_e32 v8, v22, v24
	v_add_f32_e32 v9, v18, v20
	v_add_f32_e32 v8, v8, v23
	v_add_f32_e32 v9, v9, v19
	v_add_f32_e32 v8, v25, v8
	v_add_f32_e32 v9, v21, v9
	v_pk_mul_f32 v[0:1], v[4:5], v[4:5]
	v_pk_mul_f32 v[6:7], v[2:3], v[2:3]
	v_add_f32_e32 v8, v9, v8
	v_add_f32_e32 v9, v26, v28
	v_add_f32_e32 v9, v9, v27
	v_add_f32_e32 v0, v0, v6
	v_add_f32_e32 v9, v29, v9
	v_add_f32_e32 v0, v0, v1
	v_add_f32_e32 v8, v8, v9
	v_add_f32_e32 v0, v7, v0
	v_add_f32_e32 v0, v8, v0
	v_and_b32_sdwa v6, v4, v103 dst_sel:DWORD dst_unused:UNUSED_PAD src0_sel:WORD_1 src1_sel:DWORD
	v_add3_u32 v4, v4, v6, s16
	ds_bpermute_b32 v6, v53, v0
	v_and_b32_sdwa v1, v5, v103 dst_sel:DWORD dst_unused:UNUSED_PAD src0_sel:WORD_1 src1_sel:DWORD
	v_add3_u32 v5, v5, v1, s16
	v_and_b32_sdwa v1, v3, v103 dst_sel:DWORD dst_unused:UNUSED_PAD src0_sel:WORD_1 src1_sel:DWORD
	v_add3_u32 v1, v3, v1, s16
	s_waitcnt lgkmcnt(0)
	v_add_f32_e32 v0, v0, v6
	v_and_b32_e32 v3, 0xffff0000, v1
	ds_bpermute_b32 v1, v52, v0
	v_and_b32_sdwa v7, v2, v103 dst_sel:DWORD dst_unused:UNUSED_PAD src0_sel:WORD_1 src1_sel:DWORD
	v_add3_u32 v2, v2, v7, s16
	v_and_b32_e32 v2, 0xffff0000, v2
	v_or_b32_sdwa v3, v3, v5 dst_sel:DWORD dst_unused:UNUSED_PAD src0_sel:DWORD src1_sel:WORD_1
	v_or_b32_sdwa v2, v2, v4 dst_sel:DWORD dst_unused:UNUSED_PAD src0_sel:DWORD src1_sel:WORD_1
	ds_write_b64 v183, v[2:3] offset:6144
	s_waitcnt lgkmcnt(0)
	ds_read_b128 v[212:215], v184 offset:0
	ds_read_b128 v[216:219], v184 offset:1024
	ds_read_b128 v[220:223], v184 offset:2048
	ds_read_b128 v[224:227], v184 offset:3072
	ds_read_b128 v[228:231], v184 offset:4096
	ds_read_b128 v[232:235], v184 offset:5120
	ds_read_b128 v[236:239], v184 offset:6144
	ds_read_b128 v[240:243], v184 offset:7168
	s_waitcnt lgkmcnt(7)
	global_store_dwordx4 v185, v[212:215], s[98:99]
	v_add_u32_e32 v185, v185, v186
	s_waitcnt lgkmcnt(6)
	global_store_dwordx4 v185, v[216:219], s[98:99]
	v_add_u32_e32 v185, v185, v186
	s_waitcnt lgkmcnt(5)
	global_store_dwordx4 v185, v[220:223], s[98:99]
	v_add_u32_e32 v185, v185, v186
	s_waitcnt lgkmcnt(4)
	global_store_dwordx4 v185, v[224:227], s[98:99]
	v_add_u32_e32 v185, v185, v186
	s_waitcnt lgkmcnt(3)
	global_store_dwordx4 v185, v[228:231], s[98:99]
	v_add_u32_e32 v185, v185, v186
	s_waitcnt lgkmcnt(2)
	global_store_dwordx4 v185, v[232:235], s[98:99]
	v_add_u32_e32 v185, v185, v186
	s_waitcnt lgkmcnt(1)
	global_store_dwordx4 v185, v[236:239], s[98:99]
	v_add_u32_e32 v185, v185, v186
	s_waitcnt lgkmcnt(0)
	global_store_dwordx4 v185, v[240:243], s[98:99]
	s_barrier
	s_and_saveexec_b64 s[4:5], vcc
	s_cbranch_execz .LBB0_1088
	s_waitcnt lgkmcnt(0)
	v_add_f32_e32 v0, v0, v1
	global_atomic_add_f32 v[48:49], v0, off offset:192
	s_branch .LBB0_1088
